# code placement: .p2align 6 before each GEMM K-loop header (on top of v20)
# baseline (speedup 1.0000x reference)
.LBB0_196:
	s_ashr_i32 s17, s16, 31
	s_lshl_b64 s[18:19], s[16:17], 19
	v_readlane_b32 s15, v252, 39
	s_add_u32 s18, s15, s18
	s_addc_u32 s19, s71, s19
	s_and_b64 s[20:21], s[4:5], exec
	s_cselect_b32 s17, s19, s37
	s_cselect_b32 s23, s18, s36
	s_ashr_i32 s15, s14, 31
	s_lshl_b64 s[20:21], s[14:15], 19
	s_add_u32 s20, s34, s20
	s_addc_u32 s21, s35, s21
	s_and_b64 s[40:41], s[4:5], exec
	s_cselect_b32 s15, s21, s39
	s_cselect_b32 s59, s20, s38
	s_add_u32 s36, s36, 0x40080
	s_addc_u32 s37, s37, 0
	s_add_u32 s60, s38, 0x100
	v_mov_b32_e32 v0, 0
	s_addc_u32 s61, s39, 0
	s_mov_b32 s62, -2
	v_mov_b32_e32 v1, v0
	v_mov_b32_e32 v2, v0
	v_mov_b32_e32 v3, v0
	v_mov_b32_e32 v4, v0
	v_mov_b32_e32 v5, v0
	v_mov_b32_e32 v6, v0
	v_mov_b32_e32 v7, v0
	v_mov_b32_e32 v16, v0
	v_mov_b32_e32 v17, v0
	v_mov_b32_e32 v18, v0
	v_mov_b32_e32 v19, v0
	v_mov_b32_e32 v20, v0
	v_mov_b32_e32 v21, v0
	v_mov_b32_e32 v22, v0
	v_mov_b32_e32 v23, v0
	v_mov_b32_e32 v32, v0
	v_mov_b32_e32 v33, v0
	v_mov_b32_e32 v34, v0
	v_mov_b32_e32 v35, v0
	v_mov_b32_e32 v36, v0
	v_mov_b32_e32 v37, v0
	v_mov_b32_e32 v38, v0
	v_mov_b32_e32 v39, v0
	v_mov_b32_e32 v48, v0
	v_mov_b32_e32 v49, v0
	v_mov_b32_e32 v50, v0
	v_mov_b32_e32 v51, v0
	v_mov_b32_e32 v52, v0
	v_mov_b32_e32 v53, v0
	v_mov_b32_e32 v54, v0
	v_mov_b32_e32 v55, v0
	v_mov_b32_e32 v8, v0
	v_mov_b32_e32 v9, v0
	v_mov_b32_e32 v10, v0
	v_mov_b32_e32 v11, v0
	v_mov_b32_e32 v12, v0
	v_mov_b32_e32 v13, v0
	v_mov_b32_e32 v14, v0
	v_mov_b32_e32 v15, v0
	v_mov_b32_e32 v24, v0
	v_mov_b32_e32 v25, v0
	v_mov_b32_e32 v26, v0
	v_mov_b32_e32 v27, v0
	v_mov_b32_e32 v28, v0
	v_mov_b32_e32 v29, v0
	v_mov_b32_e32 v30, v0
	v_mov_b32_e32 v31, v0
	v_mov_b32_e32 v40, v0
	v_mov_b32_e32 v41, v0
	v_mov_b32_e32 v42, v0
	v_mov_b32_e32 v43, v0
	v_mov_b32_e32 v44, v0
	v_mov_b32_e32 v45, v0
	v_mov_b32_e32 v46, v0
	v_mov_b32_e32 v47, v0
	v_mov_b32_e32 v56, v0
	v_mov_b32_e32 v57, v0
	v_mov_b32_e32 v58, v0
	v_mov_b32_e32 v59, v0
	v_mov_b32_e32 v60, v0
	v_mov_b32_e32 v61, v0
	v_mov_b32_e32 v62, v0
	v_mov_b32_e32 v63, v0
	v_mov_b32_e32 v64, v0
	v_mov_b32_e32 v65, v0
	v_mov_b32_e32 v66, v0
	v_mov_b32_e32 v67, v0
	v_mov_b32_e32 v68, v0
	v_mov_b32_e32 v69, v0
	v_mov_b32_e32 v70, v0
	v_mov_b32_e32 v71, v0
	v_mov_b32_e32 v80, v0
	v_mov_b32_e32 v81, v0
	v_mov_b32_e32 v82, v0
	v_mov_b32_e32 v83, v0
	v_mov_b32_e32 v84, v0
	v_mov_b32_e32 v85, v0
	v_mov_b32_e32 v86, v0
	v_mov_b32_e32 v87, v0
	v_mov_b32_e32 v96, v0
	v_mov_b32_e32 v97, v0
	v_mov_b32_e32 v98, v0
	v_mov_b32_e32 v99, v0
	v_mov_b32_e32 v100, v0
	v_mov_b32_e32 v101, v0
	v_mov_b32_e32 v102, v0
	v_mov_b32_e32 v103, v0
	v_mov_b32_e32 v104, v0
	v_mov_b32_e32 v105, v0
	v_mov_b32_e32 v106, v0
	v_mov_b32_e32 v107, v0
	v_mov_b32_e32 v108, v0
	v_mov_b32_e32 v109, v0
	v_mov_b32_e32 v110, v0
	v_mov_b32_e32 v111, v0
	v_mov_b32_e32 v72, v0
	v_mov_b32_e32 v73, v0
	v_mov_b32_e32 v74, v0
	v_mov_b32_e32 v75, v0
	v_mov_b32_e32 v76, v0
	v_mov_b32_e32 v77, v0
	v_mov_b32_e32 v78, v0
	v_mov_b32_e32 v79, v0
	v_mov_b32_e32 v88, v0
	v_mov_b32_e32 v89, v0
	v_mov_b32_e32 v90, v0
	v_mov_b32_e32 v91, v0
	v_mov_b32_e32 v92, v0
	v_mov_b32_e32 v93, v0
	v_mov_b32_e32 v94, v0
	v_mov_b32_e32 v95, v0
	v_mov_b32_e32 v112, v0
	v_mov_b32_e32 v113, v0
	v_mov_b32_e32 v114, v0
	v_mov_b32_e32 v115, v0
	v_mov_b32_e32 v116, v0
	v_mov_b32_e32 v117, v0
	v_mov_b32_e32 v118, v0
	v_mov_b32_e32 v119, v0
	v_mov_b32_e32 v120, v0
	v_mov_b32_e32 v121, v0
	v_mov_b32_e32 v122, v0
	v_mov_b32_e32 v123, v0
	v_mov_b32_e32 v124, v0
	v_mov_b32_e32 v125, v0
	v_mov_b32_e32 v126, v0
	v_mov_b32_e32 v127, v0
	.p2align 6

.Lrb0_skip:
	s_add_u32 s48, s46, 0xfffc0080
	s_addc_u32 s49, s47, -1
	s_add_i32 s63, 0, 0x10000
	s_cmp_eq_u32 s62, 12
	s_cselect_b32 s51, s39, s49
	s_cselect_b32 s50, s58, s48
	v_add_u32_e32 v0, s63, v144
	s_cselect_b32 s49, s23, s61
	s_cselect_b32 s48, s59, s60
	s_add_i32 s66, 0, 0x14000
	ds_read_b128 v[146:149], v0
	ds_read_b128 v[150:153], v0 offset:1024
	ds_read_b128 v[154:157], v0 offset:2048
	ds_read_b128 v[158:161], v0 offset:3072
	v_add_u32_e32 v0, s66, v144
	ds_read_b128 v[162:165], v0
	ds_read_b128 v[166:169], v0 offset:1024
	ds_read_b128 v[170:173], v0 offset:2048
	ds_read_b128 v[174:177], v0 offset:3072
	s_add_i32 m0, s5, 0xc000
	ds_read_b128 v[178:181], v145
	ds_read_b128 v[182:185], v145 offset:1024
	ds_read_b128 v[204:207], v145 offset:2048
	ds_read_b128 v[208:211], v145 offset:3072
	ds_read_b128 v[212:215], v145 offset:4096
	ds_read_b128 v[216:219], v145 offset:5120
	ds_read_b128 v[220:223], v145 offset:6144
	ds_read_b128 v[224:227], v145 offset:7168
	global_load_lds_dwordx4 v138, s[46:47]
	s_add_i32 m0, s5, 0xe000
	s_nop 0
	global_load_lds_dwordx4 v140, s[46:47]
	s_waitcnt vmcnt(8)
	s_waitcnt lgkmcnt(0)
	s_setprio 1
	s_barrier
	v_mfma_f32_16x16x32_bf16 v[118:121], v[146:149], v[178:181], 0
	v_mfma_f32_16x16x32_bf16 v[114:117], v[154:157], v[178:181], 0
	v_mfma_f32_16x16x32_bf16 v[110:113], v[146:149], v[204:207], 0
	v_mfma_f32_16x16x32_bf16 v[102:105], v[154:157], v[204:207], 0
	v_mfma_f32_16x16x32_bf16 v[94:97], v[146:149], v[212:215], 0
	v_mfma_f32_16x16x32_bf16 v[86:89], v[154:157], v[212:215], 0
	v_mfma_f32_16x16x32_bf16 v[78:81], v[146:149], v[220:223], 0
	v_mfma_f32_16x16x32_bf16 v[70:73], v[154:157], v[220:223], 0
	v_mfma_f32_16x16x32_bf16 v[118:121], v[150:153], v[182:185], v[118:121]
	v_mfma_f32_16x16x32_bf16 v[114:117], v[158:161], v[182:185], v[114:117]
	v_mfma_f32_16x16x32_bf16 v[110:113], v[150:153], v[208:211], v[110:113]
	v_mfma_f32_16x16x32_bf16 v[102:105], v[158:161], v[208:211], v[102:105]
	v_mfma_f32_16x16x32_bf16 v[94:97], v[150:153], v[216:219], v[94:97]
	v_mfma_f32_16x16x32_bf16 v[86:89], v[158:161], v[216:219], v[86:89]
	v_mfma_f32_16x16x32_bf16 v[78:81], v[150:153], v[224:227], v[78:81]
	v_mfma_f32_16x16x32_bf16 v[70:73], v[158:161], v[224:227], v[70:73]
	v_mfma_f32_16x16x32_bf16 v[126:129], v[162:165], v[178:181], 0
	v_mfma_f32_16x16x32_bf16 v[122:125], v[170:173], v[178:181], 0
	v_mfma_f32_16x16x32_bf16 v[106:109], v[162:165], v[204:207], 0
	v_mfma_f32_16x16x32_bf16 v[98:101], v[170:173], v[204:207], 0
	v_mfma_f32_16x16x32_bf16 v[90:93], v[162:165], v[212:215], 0
	v_mfma_f32_16x16x32_bf16 v[82:85], v[170:173], v[212:215], 0
	v_mfma_f32_16x16x32_bf16 v[74:77], v[162:165], v[220:223], 0
	v_mfma_f32_16x16x32_bf16 v[66:69], v[170:173], v[220:223], 0
	v_mfma_f32_16x16x32_bf16 v[126:129], v[166:169], v[182:185], v[126:129]
	v_mfma_f32_16x16x32_bf16 v[122:125], v[174:177], v[182:185], v[122:125]
	v_mfma_f32_16x16x32_bf16 v[106:109], v[166:169], v[208:211], v[106:109]
	v_mfma_f32_16x16x32_bf16 v[98:101], v[174:177], v[208:211], v[98:101]
	v_mfma_f32_16x16x32_bf16 v[90:93], v[166:169], v[216:219], v[90:93]
	v_mfma_f32_16x16x32_bf16 v[82:85], v[174:177], v[216:219], v[82:85]
	v_mfma_f32_16x16x32_bf16 v[74:77], v[166:169], v[224:227], v[74:77]
	v_mfma_f32_16x16x32_bf16 v[66:69], v[174:177], v[224:227], v[66:69]
	s_barrier
	s_setprio 0
	s_add_i32 s63, s63, s4
	s_mov_b32 m0, s63
	ds_read_b128 v[178:181], v145 offset:16384
	ds_read_b128 v[182:185], v145 offset:17408
	ds_read_b128 v[204:207], v145 offset:18432
	ds_read_b128 v[208:211], v145 offset:19456
	ds_read_b128 v[212:215], v145 offset:20480
	ds_read_b128 v[216:219], v145 offset:21504
	ds_read_b128 v[220:223], v145 offset:22528
	ds_read_b128 v[224:227], v145 offset:23552
	global_load_lds_dwordx4 v134, s[48:49]
	s_add_i32 m0, s63, 0x2000
	s_add_u32 s64, s48, 0x40000
	s_addc_u32 s65, s49, 0
	s_add_i32 s63, s66, s4
	global_load_lds_dwordx4 v130, s[48:49]
	s_mov_b32 m0, s63
	s_nop 0
	global_load_lds_dwordx4 v134, s[64:65]
	s_add_i32 m0, s63, 0x2000
	s_nop 0
	global_load_lds_dwordx4 v130, s[64:65]
	s_mov_b32 m0, s5
	s_nop 0
	global_load_lds_dwordx4 v136, s[50:51]
	s_mov_b32 m0, s6
	s_nop 0
	global_load_lds_dwordx4 v132, s[50:51]
	s_waitcnt vmcnt(8)
	s_waitcnt lgkmcnt(0)
	s_setprio 1
	s_barrier
	v_mfma_f32_16x16x32_bf16 v[62:65], v[146:149], v[178:181], 0
	v_mfma_f32_16x16x32_bf16 v[54:57], v[154:157], v[178:181], 0
	v_mfma_f32_16x16x32_bf16 v[46:49], v[146:149], v[204:207], 0
	v_mfma_f32_16x16x32_bf16 v[38:41], v[154:157], v[204:207], 0
	v_mfma_f32_16x16x32_bf16 v[30:33], v[146:149], v[212:215], 0
	v_mfma_f32_16x16x32_bf16 v[22:25], v[154:157], v[212:215], 0
	v_mfma_f32_16x16x32_bf16 v[14:17], v[146:149], v[220:223], 0
	v_mfma_f32_16x16x32_bf16 v[6:9], v[154:157], v[220:223], 0
	v_mfma_f32_16x16x32_bf16 v[62:65], v[150:153], v[182:185], v[62:65]
	v_mfma_f32_16x16x32_bf16 v[54:57], v[158:161], v[182:185], v[54:57]
	v_mfma_f32_16x16x32_bf16 v[46:49], v[150:153], v[208:211], v[46:49]
	v_mfma_f32_16x16x32_bf16 v[38:41], v[158:161], v[208:211], v[38:41]
	v_mfma_f32_16x16x32_bf16 v[30:33], v[150:153], v[216:219], v[30:33]
	v_mfma_f32_16x16x32_bf16 v[22:25], v[158:161], v[216:219], v[22:25]
	v_mfma_f32_16x16x32_bf16 v[14:17], v[150:153], v[224:227], v[14:17]
	v_mfma_f32_16x16x32_bf16 v[6:9], v[158:161], v[224:227], v[6:9]
	v_mfma_f32_16x16x32_bf16 v[58:61], v[162:165], v[178:181], 0
	v_mfma_f32_16x16x32_bf16 v[50:53], v[170:173], v[178:181], 0
	v_mfma_f32_16x16x32_bf16 v[42:45], v[162:165], v[204:207], 0
	v_mfma_f32_16x16x32_bf16 v[34:37], v[170:173], v[204:207], 0
	v_mfma_f32_16x16x32_bf16 v[26:29], v[162:165], v[212:215], 0
	v_mfma_f32_16x16x32_bf16 v[18:21], v[170:173], v[212:215], 0
	v_mfma_f32_16x16x32_bf16 v[10:13], v[162:165], v[220:223], 0
	v_mfma_f32_16x16x32_bf16 v[2:5], v[170:173], v[220:223], 0
	v_mfma_f32_16x16x32_bf16 v[58:61], v[166:169], v[182:185], v[58:61]
	v_mfma_f32_16x16x32_bf16 v[50:53], v[174:177], v[182:185], v[50:53]
	v_mfma_f32_16x16x32_bf16 v[42:45], v[166:169], v[208:211], v[42:45]
	v_mfma_f32_16x16x32_bf16 v[34:37], v[174:177], v[208:211], v[34:37]
	v_mfma_f32_16x16x32_bf16 v[26:29], v[166:169], v[216:219], v[26:29]
	v_mfma_f32_16x16x32_bf16 v[18:21], v[174:177], v[216:219], v[18:21]
	v_mfma_f32_16x16x32_bf16 v[10:13], v[166:169], v[224:227], v[10:13]
	v_mfma_f32_16x16x32_bf16 v[2:5], v[174:177], v[224:227], v[2:5]
	s_barrier
	s_setprio 0
	s_add_i32 s63, 0, 0x18000
	v_add_u32_e32 v0, s63, v144
	s_add_i32 s64, 0, 0x1c000
	ds_read_b128 v[146:149], v0
	ds_read_b128 v[150:153], v0 offset:1024
	ds_read_b128 v[154:157], v0 offset:2048
	ds_read_b128 v[158:161], v0 offset:3072
	v_add_u32_e32 v0, s64, v144
	ds_read_b128 v[162:165], v0
	ds_read_b128 v[166:169], v0 offset:1024
	ds_read_b128 v[170:173], v0 offset:2048
	ds_read_b128 v[174:177], v0 offset:3072
	s_add_u32 s50, s50, 0x40000
	s_addc_u32 s51, s51, 0
	s_mov_b32 m0, s7
	ds_read_b128 v[178:181], v145 offset:32768
	ds_read_b128 v[182:185], v145 offset:33792
	ds_read_b128 v[204:207], v145 offset:34816
	ds_read_b128 v[208:211], v145 offset:35840
	ds_read_b128 v[212:215], v145 offset:36864
	ds_read_b128 v[216:219], v145 offset:37888
	ds_read_b128 v[220:223], v145 offset:38912
	ds_read_b128 v[224:227], v145 offset:39936
	global_load_lds_dwordx4 v136, s[50:51]
	s_mov_b32 m0, s52
	s_nop 0
	global_load_lds_dwordx4 v132, s[50:51]
	s_waitcnt vmcnt(8)
	s_waitcnt lgkmcnt(0)
	s_setprio 1
	s_barrier
	v_mfma_f32_16x16x32_bf16 v[118:121], v[146:149], v[178:181], v[118:121]
	v_mfma_f32_16x16x32_bf16 v[114:117], v[154:157], v[178:181], v[114:117]
	v_mfma_f32_16x16x32_bf16 v[110:113], v[146:149], v[204:207], v[110:113]
	v_mfma_f32_16x16x32_bf16 v[102:105], v[154:157], v[204:207], v[102:105]
	v_mfma_f32_16x16x32_bf16 v[94:97], v[146:149], v[212:215], v[94:97]
	v_mfma_f32_16x16x32_bf16 v[86:89], v[154:157], v[212:215], v[86:89]
	v_mfma_f32_16x16x32_bf16 v[78:81], v[146:149], v[220:223], v[78:81]
	v_mfma_f32_16x16x32_bf16 v[70:73], v[154:157], v[220:223], v[70:73]
	v_mfma_f32_16x16x32_bf16 v[118:121], v[150:153], v[182:185], v[118:121]
	v_mfma_f32_16x16x32_bf16 v[114:117], v[158:161], v[182:185], v[114:117]
	v_mfma_f32_16x16x32_bf16 v[110:113], v[150:153], v[208:211], v[110:113]
	v_mfma_f32_16x16x32_bf16 v[102:105], v[158:161], v[208:211], v[102:105]
	v_mfma_f32_16x16x32_bf16 v[94:97], v[150:153], v[216:219], v[94:97]
	v_mfma_f32_16x16x32_bf16 v[86:89], v[158:161], v[216:219], v[86:89]
	v_mfma_f32_16x16x32_bf16 v[78:81], v[150:153], v[224:227], v[78:81]
	v_mfma_f32_16x16x32_bf16 v[70:73], v[158:161], v[224:227], v[70:73]
	v_mfma_f32_16x16x32_bf16 v[126:129], v[162:165], v[178:181], v[126:129]
	v_mfma_f32_16x16x32_bf16 v[122:125], v[170:173], v[178:181], v[122:125]
	v_mfma_f32_16x16x32_bf16 v[106:109], v[162:165], v[204:207], v[106:109]
	v_mfma_f32_16x16x32_bf16 v[98:101], v[170:173], v[204:207], v[98:101]
	v_mfma_f32_16x16x32_bf16 v[90:93], v[162:165], v[212:215], v[90:93]
	v_mfma_f32_16x16x32_bf16 v[82:85], v[170:173], v[212:215], v[82:85]
	v_mfma_f32_16x16x32_bf16 v[74:77], v[162:165], v[220:223], v[74:77]
	v_mfma_f32_16x16x32_bf16 v[66:69], v[170:173], v[220:223], v[66:69]
	v_mfma_f32_16x16x32_bf16 v[126:129], v[166:169], v[182:185], v[126:129]
	v_mfma_f32_16x16x32_bf16 v[122:125], v[174:177], v[182:185], v[122:125]
	v_mfma_f32_16x16x32_bf16 v[106:109], v[166:169], v[208:211], v[106:109]
	v_mfma_f32_16x16x32_bf16 v[98:101], v[174:177], v[208:211], v[98:101]
	v_mfma_f32_16x16x32_bf16 v[90:93], v[166:169], v[216:219], v[90:93]
	v_mfma_f32_16x16x32_bf16 v[82:85], v[174:177], v[216:219], v[82:85]
	v_mfma_f32_16x16x32_bf16 v[74:77], v[166:169], v[224:227], v[74:77]
	v_mfma_f32_16x16x32_bf16 v[66:69], v[174:177], v[224:227], v[66:69]
	s_barrier
	s_setprio 0
	s_add_i32 s65, s63, s4
	s_add_u32 s48, s48, 0x80
	s_addc_u32 s49, s49, 0
	s_mov_b32 m0, s65
	ds_read_b128 v[178:181], v145 offset:49152
	ds_read_b128 v[182:185], v145 offset:50176
	ds_read_b128 v[204:207], v145 offset:51200
	ds_read_b128 v[208:211], v145 offset:52224
	ds_read_b128 v[212:215], v145 offset:53248
	ds_read_b128 v[216:219], v145 offset:54272
	ds_read_b128 v[220:223], v145 offset:55296
	ds_read_b128 v[224:227], v145 offset:56320
	global_load_lds_dwordx4 v134, s[48:49]
	s_add_i32 m0, s65, 0x2000
	s_add_i32 s65, s64, s4
	global_load_lds_dwordx4 v130, s[48:49]
	s_add_u32 s48, s48, 0x40000
	s_addc_u32 s49, s49, 0
	s_mov_b32 m0, s65
	s_sub_u32 s50, s50, 0x3ff80
	global_load_lds_dwordx4 v134, s[48:49]
	s_subb_u32 s51, s51, 0
	s_add_i32 m0, s65, 0x2000
	s_nop 0
	global_load_lds_dwordx4 v130, s[48:49]
	s_mov_b32 m0, s55
	s_nop 0
	global_load_lds_dwordx4 v136, s[50:51]
	s_mov_b32 m0, s56
	s_nop 0
	global_load_lds_dwordx4 v132, s[50:51]
	s_waitcnt vmcnt(8)
	s_waitcnt lgkmcnt(0)
	s_setprio 1
	s_barrier
	v_mfma_f32_16x16x32_bf16 v[62:65], v[146:149], v[178:181], v[62:65]
	v_mfma_f32_16x16x32_bf16 v[54:57], v[154:157], v[178:181], v[54:57]
	v_mfma_f32_16x16x32_bf16 v[46:49], v[146:149], v[204:207], v[46:49]
	v_mfma_f32_16x16x32_bf16 v[38:41], v[154:157], v[204:207], v[38:41]
	v_mfma_f32_16x16x32_bf16 v[30:33], v[146:149], v[212:215], v[30:33]
	v_mfma_f32_16x16x32_bf16 v[22:25], v[154:157], v[212:215], v[22:25]
	v_mfma_f32_16x16x32_bf16 v[14:17], v[146:149], v[220:223], v[14:17]
	v_mfma_f32_16x16x32_bf16 v[6:9], v[154:157], v[220:223], v[6:9]
	v_mfma_f32_16x16x32_bf16 v[62:65], v[150:153], v[182:185], v[62:65]
	v_mfma_f32_16x16x32_bf16 v[54:57], v[158:161], v[182:185], v[54:57]
	v_mfma_f32_16x16x32_bf16 v[46:49], v[150:153], v[208:211], v[46:49]
	v_mfma_f32_16x16x32_bf16 v[38:41], v[158:161], v[208:211], v[38:41]
	v_mfma_f32_16x16x32_bf16 v[30:33], v[150:153], v[216:219], v[30:33]
	v_mfma_f32_16x16x32_bf16 v[22:25], v[158:161], v[216:219], v[22:25]
	v_mfma_f32_16x16x32_bf16 v[14:17], v[150:153], v[224:227], v[14:17]
	v_mfma_f32_16x16x32_bf16 v[6:9], v[158:161], v[224:227], v[6:9]
	v_mfma_f32_16x16x32_bf16 v[58:61], v[162:165], v[178:181], v[58:61]
	v_mfma_f32_16x16x32_bf16 v[50:53], v[170:173], v[178:181], v[50:53]
	v_mfma_f32_16x16x32_bf16 v[42:45], v[162:165], v[204:207], v[42:45]
	v_mfma_f32_16x16x32_bf16 v[34:37], v[170:173], v[204:207], v[34:37]
	v_mfma_f32_16x16x32_bf16 v[26:29], v[162:165], v[212:215], v[26:29]
	v_mfma_f32_16x16x32_bf16 v[18:21], v[170:173], v[212:215], v[18:21]
	v_mfma_f32_16x16x32_bf16 v[10:13], v[162:165], v[220:223], v[10:13]
	v_mfma_f32_16x16x32_bf16 v[2:5], v[170:173], v[220:223], v[2:5]
	v_mfma_f32_16x16x32_bf16 v[58:61], v[166:169], v[182:185], v[58:61]
	v_mfma_f32_16x16x32_bf16 v[50:53], v[174:177], v[182:185], v[50:53]
	v_mfma_f32_16x16x32_bf16 v[42:45], v[166:169], v[208:211], v[42:45]
	v_mfma_f32_16x16x32_bf16 v[34:37], v[174:177], v[208:211], v[34:37]
	v_mfma_f32_16x16x32_bf16 v[26:29], v[166:169], v[216:219], v[26:29]
	v_mfma_f32_16x16x32_bf16 v[18:21], v[174:177], v[216:219], v[18:21]
	v_mfma_f32_16x16x32_bf16 v[10:13], v[166:169], v[224:227], v[10:13]
	v_mfma_f32_16x16x32_bf16 v[2:5], v[174:177], v[224:227], v[2:5]
	s_barrier
	s_setprio 0
	s_add_i32 s62, s62, 2
	s_add_u32 s46, s46, 0x100
	s_addc_u32 s47, s47, 0
	s_add_u32 s60, s60, 0x100
	s_addc_u32 s61, s61, 0
	s_cmp_gt_u32 s62, 13
	.p2align 6

.Lrb1_skip:
	s_add_u32 s0, s48, 0x100
	s_addc_u32 s1, s49, 0
	s_add_i32 s51, 0, 0x10000
	s_cmp_eq_u32 s19, 40
	s_cselect_b32 s55, s45, s1
	s_cselect_b32 s54, s44, s0
	v_add_u32_e32 v0, s51, v219
	s_cselect_b32 s53, s47, s18
	s_cselect_b32 s52, s46, s7
	s_add_i32 s66, 0, 0x14000
	ds_read_b128 v[106:109], v0
	ds_read_b128 v[110:113], v0 offset:1024
	ds_read_b128 v[126:129], v0 offset:2048
	ds_read_b128 v[134:137], v0 offset:3072
	v_add_u32_e32 v0, s66, v219
	ds_read_b128 v[146:149], v0
	ds_read_b128 v[150:153], v0 offset:1024
	ds_read_b128 v[154:157], v0 offset:2048
	ds_read_b128 v[158:161], v0 offset:3072
	v_lshl_add_u64 v[216:217], s[48:49], 0, v[212:213]
	s_add_i32 m0, s57, 0xc000
	ds_read_b128 v[162:165], v220
	ds_read_b128 v[166:169], v220 offset:1024
	ds_read_b128 v[170:173], v220 offset:2048
	ds_read_b128 v[174:177], v220 offset:3072
	ds_read_b128 v[178:181], v220 offset:4096
	ds_read_b128 v[182:185], v220 offset:5120
	ds_read_b128 v[222:225], v220 offset:6144
	ds_read_b128 v[226:229], v220 offset:7168
	global_load_lds_dwordx4 v[216:217], off
	v_lshl_add_u64 v[216:217], s[48:49], 0, v[214:215]
	s_add_i32 m0, s57, 0xe000
	s_nop 0
	global_load_lds_dwordx4 v[216:217], off
	s_waitcnt vmcnt(8)
	s_waitcnt lgkmcnt(0)
	s_setprio 1
	s_barrier
	v_mfma_f32_16x16x32_bf16 v[142:145], v[106:109], v[162:165], 0
	v_mfma_f32_16x16x32_bf16 v[138:141], v[126:129], v[162:165], 0
	v_mfma_f32_16x16x32_bf16 v[118:121], v[106:109], v[170:173], 0
	v_mfma_f32_16x16x32_bf16 v[114:117], v[126:129], v[170:173], 0
	v_mfma_f32_16x16x32_bf16 v[94:97], v[106:109], v[178:181], 0
	v_mfma_f32_16x16x32_bf16 v[90:93], v[126:129], v[178:181], 0
	v_mfma_f32_16x16x32_bf16 v[78:81], v[106:109], v[222:225], 0
	v_mfma_f32_16x16x32_bf16 v[74:77], v[126:129], v[222:225], 0
	v_mfma_f32_16x16x32_bf16 v[142:145], v[110:113], v[166:169], v[142:145]
	v_mfma_f32_16x16x32_bf16 v[138:141], v[134:137], v[166:169], v[138:141]
	v_mfma_f32_16x16x32_bf16 v[118:121], v[110:113], v[174:177], v[118:121]
	v_mfma_f32_16x16x32_bf16 v[114:117], v[134:137], v[174:177], v[114:117]
	v_mfma_f32_16x16x32_bf16 v[94:97], v[110:113], v[182:185], v[94:97]
	v_mfma_f32_16x16x32_bf16 v[90:93], v[134:137], v[182:185], v[90:93]
	v_mfma_f32_16x16x32_bf16 v[78:81], v[110:113], v[226:229], v[78:81]
	v_mfma_f32_16x16x32_bf16 v[74:77], v[134:137], v[226:229], v[74:77]
	v_mfma_f32_16x16x32_bf16 v[130:133], v[146:149], v[162:165], 0
	v_mfma_f32_16x16x32_bf16 v[122:125], v[154:157], v[162:165], 0
	v_mfma_f32_16x16x32_bf16 v[102:105], v[146:149], v[170:173], 0
	v_mfma_f32_16x16x32_bf16 v[98:101], v[154:157], v[170:173], 0
	v_mfma_f32_16x16x32_bf16 v[86:89], v[146:149], v[178:181], 0
	v_mfma_f32_16x16x32_bf16 v[82:85], v[154:157], v[178:181], 0
	v_mfma_f32_16x16x32_bf16 v[70:73], v[146:149], v[222:225], 0
	v_mfma_f32_16x16x32_bf16 v[66:69], v[154:157], v[222:225], 0
	v_mfma_f32_16x16x32_bf16 v[130:133], v[150:153], v[166:169], v[130:133]
	v_mfma_f32_16x16x32_bf16 v[122:125], v[158:161], v[166:169], v[122:125]
	v_mfma_f32_16x16x32_bf16 v[102:105], v[150:153], v[174:177], v[102:105]
	v_mfma_f32_16x16x32_bf16 v[98:101], v[158:161], v[174:177], v[98:101]
	v_mfma_f32_16x16x32_bf16 v[86:89], v[150:153], v[182:185], v[86:89]
	v_mfma_f32_16x16x32_bf16 v[82:85], v[158:161], v[182:185], v[82:85]
	v_mfma_f32_16x16x32_bf16 v[70:73], v[150:153], v[226:229], v[70:73]
	v_mfma_f32_16x16x32_bf16 v[66:69], v[158:161], v[226:229], v[66:69]
	s_barrier
	s_setprio 0
	s_add_i32 s48, s51, s56
	v_lshl_add_u64 v[216:217], s[52:53], 0, v[208:209]
	s_mov_b32 m0, s48
	ds_read_b128 v[162:165], v220 offset:16384
	ds_read_b128 v[166:169], v220 offset:17408
	ds_read_b128 v[170:173], v220 offset:18432
	ds_read_b128 v[174:177], v220 offset:19456
	ds_read_b128 v[178:181], v220 offset:20480
	ds_read_b128 v[182:185], v220 offset:21504
	ds_read_b128 v[222:225], v220 offset:22528
	ds_read_b128 v[226:229], v220 offset:23552
	global_load_lds_dwordx4 v[216:217], off
	s_add_i32 m0, s48, 0x2000
	s_add_u32 s48, s52, 0xb0000
	v_lshl_add_u64 v[230:231], s[52:53], 0, v[204:205]
	s_addc_u32 s49, s53, 0
	s_add_i32 s51, s66, s56
	global_load_lds_dwordx4 v[230:231], off
	v_lshl_add_u64 v[240:241], s[48:49], 0, v[208:209]
	s_mov_b32 m0, s51
	v_lshl_add_u64 v[242:243], s[54:55], 0, v[206:207]
	global_load_lds_dwordx4 v[240:241], off
	v_lshl_add_u64 v[240:241], s[48:49], 0, v[204:205]
	s_add_i32 m0, s51, 0x2000
	s_nop 0
	global_load_lds_dwordx4 v[240:241], off
	v_lshl_add_u64 v[240:241], s[54:55], 0, v[210:211]
	s_mov_b32 m0, s57
	s_nop 0
	global_load_lds_dwordx4 v[240:241], off
	s_mov_b32 m0, s58
	s_nop 0
	global_load_lds_dwordx4 v[242:243], off
	s_waitcnt vmcnt(8)
	s_waitcnt lgkmcnt(0)
	s_setprio 1
	s_barrier
	v_mfma_f32_16x16x32_bf16 v[62:65], v[106:109], v[162:165], 0
	v_mfma_f32_16x16x32_bf16 v[58:61], v[126:129], v[162:165], 0
	v_mfma_f32_16x16x32_bf16 v[46:49], v[106:109], v[170:173], 0
	v_mfma_f32_16x16x32_bf16 v[42:45], v[126:129], v[170:173], 0
	v_mfma_f32_16x16x32_bf16 v[30:33], v[106:109], v[178:181], 0
	v_mfma_f32_16x16x32_bf16 v[26:29], v[126:129], v[178:181], 0
	v_mfma_f32_16x16x32_bf16 v[14:17], v[106:109], v[222:225], 0
	v_mfma_f32_16x16x32_bf16 v[10:13], v[126:129], v[222:225], 0
	v_mfma_f32_16x16x32_bf16 v[62:65], v[110:113], v[166:169], v[62:65]
	v_mfma_f32_16x16x32_bf16 v[58:61], v[134:137], v[166:169], v[58:61]
	v_mfma_f32_16x16x32_bf16 v[46:49], v[110:113], v[174:177], v[46:49]
	v_mfma_f32_16x16x32_bf16 v[42:45], v[134:137], v[174:177], v[42:45]
	v_mfma_f32_16x16x32_bf16 v[30:33], v[110:113], v[182:185], v[30:33]
	v_mfma_f32_16x16x32_bf16 v[26:29], v[134:137], v[182:185], v[26:29]
	v_mfma_f32_16x16x32_bf16 v[14:17], v[110:113], v[226:229], v[14:17]
	v_mfma_f32_16x16x32_bf16 v[10:13], v[134:137], v[226:229], v[10:13]
	v_mfma_f32_16x16x32_bf16 v[54:57], v[146:149], v[162:165], 0
	v_mfma_f32_16x16x32_bf16 v[50:53], v[154:157], v[162:165], 0
	v_mfma_f32_16x16x32_bf16 v[38:41], v[146:149], v[170:173], 0
	v_mfma_f32_16x16x32_bf16 v[34:37], v[154:157], v[170:173], 0
	v_mfma_f32_16x16x32_bf16 v[22:25], v[146:149], v[178:181], 0
	v_mfma_f32_16x16x32_bf16 v[18:21], v[154:157], v[178:181], 0
	v_mfma_f32_16x16x32_bf16 v[6:9], v[146:149], v[222:225], 0
	v_mfma_f32_16x16x32_bf16 v[2:5], v[154:157], v[222:225], 0
	v_mfma_f32_16x16x32_bf16 v[54:57], v[150:153], v[166:169], v[54:57]
	v_mfma_f32_16x16x32_bf16 v[50:53], v[158:161], v[166:169], v[50:53]
	v_mfma_f32_16x16x32_bf16 v[38:41], v[150:153], v[174:177], v[38:41]
	v_mfma_f32_16x16x32_bf16 v[34:37], v[158:161], v[174:177], v[34:37]
	v_mfma_f32_16x16x32_bf16 v[22:25], v[150:153], v[182:185], v[22:25]
	v_mfma_f32_16x16x32_bf16 v[18:21], v[158:161], v[182:185], v[18:21]
	v_mfma_f32_16x16x32_bf16 v[6:9], v[150:153], v[226:229], v[6:9]
	v_mfma_f32_16x16x32_bf16 v[2:5], v[158:161], v[226:229], v[2:5]
	s_barrier
	s_setprio 0
	s_add_i32 s51, 0, 0x18000
	v_add_u32_e32 v0, s51, v219
	s_add_i32 s66, 0, 0x1c000
	ds_read_b128 v[106:109], v0
	ds_read_b128 v[110:113], v0 offset:1024
	ds_read_b128 v[126:129], v0 offset:2048
	ds_read_b128 v[134:137], v0 offset:3072
	v_add_u32_e32 v0, s66, v219
	ds_read_b128 v[146:149], v0
	ds_read_b128 v[150:153], v0 offset:1024
	ds_read_b128 v[154:157], v0 offset:2048
	ds_read_b128 v[158:161], v0 offset:3072
	s_add_u32 s48, s54, 0xb0000
	s_addc_u32 s49, s55, 0
	s_mov_b32 m0, s59
	v_lshl_add_u64 v[244:245], s[48:49], 0, v[210:211]
	ds_read_b128 v[162:165], v220 offset:32768
	ds_read_b128 v[166:169], v220 offset:33792
	ds_read_b128 v[170:173], v220 offset:34816
	ds_read_b128 v[174:177], v220 offset:35840
	ds_read_b128 v[178:181], v220 offset:36864
	ds_read_b128 v[182:185], v220 offset:37888
	ds_read_b128 v[222:225], v220 offset:38912
	ds_read_b128 v[226:229], v220 offset:39936
	global_load_lds_dwordx4 v[244:245], off
	v_lshl_add_u64 v[244:245], s[48:49], 0, v[206:207]
	s_mov_b32 m0, s60
	s_nop 0
	global_load_lds_dwordx4 v[244:245], off
	s_waitcnt vmcnt(8)
	s_waitcnt lgkmcnt(0)
	s_setprio 1
	s_barrier
	v_mfma_f32_16x16x32_bf16 v[142:145], v[106:109], v[162:165], v[142:145]
	v_mfma_f32_16x16x32_bf16 v[138:141], v[126:129], v[162:165], v[138:141]
	v_mfma_f32_16x16x32_bf16 v[118:121], v[106:109], v[170:173], v[118:121]
	v_mfma_f32_16x16x32_bf16 v[114:117], v[126:129], v[170:173], v[114:117]
	v_mfma_f32_16x16x32_bf16 v[94:97], v[106:109], v[178:181], v[94:97]
	v_mfma_f32_16x16x32_bf16 v[90:93], v[126:129], v[178:181], v[90:93]
	v_mfma_f32_16x16x32_bf16 v[78:81], v[106:109], v[222:225], v[78:81]
	v_mfma_f32_16x16x32_bf16 v[74:77], v[126:129], v[222:225], v[74:77]
	v_mfma_f32_16x16x32_bf16 v[142:145], v[110:113], v[166:169], v[142:145]
	v_mfma_f32_16x16x32_bf16 v[138:141], v[134:137], v[166:169], v[138:141]
	v_mfma_f32_16x16x32_bf16 v[118:121], v[110:113], v[174:177], v[118:121]
	v_mfma_f32_16x16x32_bf16 v[114:117], v[134:137], v[174:177], v[114:117]
	v_mfma_f32_16x16x32_bf16 v[94:97], v[110:113], v[182:185], v[94:97]
	v_mfma_f32_16x16x32_bf16 v[90:93], v[134:137], v[182:185], v[90:93]
	v_mfma_f32_16x16x32_bf16 v[78:81], v[110:113], v[226:229], v[78:81]
	v_mfma_f32_16x16x32_bf16 v[74:77], v[134:137], v[226:229], v[74:77]
	v_mfma_f32_16x16x32_bf16 v[130:133], v[146:149], v[162:165], v[130:133]
	v_mfma_f32_16x16x32_bf16 v[122:125], v[154:157], v[162:165], v[122:125]
	v_mfma_f32_16x16x32_bf16 v[102:105], v[146:149], v[170:173], v[102:105]
	v_mfma_f32_16x16x32_bf16 v[98:101], v[154:157], v[170:173], v[98:101]
	v_mfma_f32_16x16x32_bf16 v[86:89], v[146:149], v[178:181], v[86:89]
	v_mfma_f32_16x16x32_bf16 v[82:85], v[154:157], v[178:181], v[82:85]
	v_mfma_f32_16x16x32_bf16 v[70:73], v[146:149], v[222:225], v[70:73]
	v_mfma_f32_16x16x32_bf16 v[66:69], v[154:157], v[222:225], v[66:69]
	v_mfma_f32_16x16x32_bf16 v[130:133], v[150:153], v[166:169], v[130:133]
	v_mfma_f32_16x16x32_bf16 v[122:125], v[158:161], v[166:169], v[122:125]
	v_mfma_f32_16x16x32_bf16 v[102:105], v[150:153], v[174:177], v[102:105]
	v_mfma_f32_16x16x32_bf16 v[98:101], v[158:161], v[174:177], v[98:101]
	v_mfma_f32_16x16x32_bf16 v[86:89], v[150:153], v[182:185], v[86:89]
	v_mfma_f32_16x16x32_bf16 v[82:85], v[158:161], v[182:185], v[82:85]
	v_mfma_f32_16x16x32_bf16 v[70:73], v[150:153], v[226:229], v[70:73]
	v_mfma_f32_16x16x32_bf16 v[66:69], v[158:161], v[226:229], v[66:69]
	s_barrier
	s_setprio 0
	s_add_i32 s48, s51, s56
	v_lshl_add_u64 v[216:217], v[216:217], 0, s[16:17]
	s_mov_b32 m0, s48
	ds_read_b128 v[162:165], v220 offset:49152
	ds_read_b128 v[166:169], v220 offset:50176
	ds_read_b128 v[170:173], v220 offset:51200
	ds_read_b128 v[174:177], v220 offset:52224
	ds_read_b128 v[178:181], v220 offset:53248
	ds_read_b128 v[182:185], v220 offset:54272
	ds_read_b128 v[222:225], v220 offset:55296
	ds_read_b128 v[226:229], v220 offset:56320
	global_load_lds_dwordx4 v[216:217], off
	s_add_i32 m0, s48, 0x2000
	s_add_u32 s48, s52, 0xb0080
	v_lshl_add_u64 v[216:217], v[230:231], 0, s[16:17]
	s_addc_u32 s49, s53, 0
	s_add_i32 s51, s66, s56
	global_load_lds_dwordx4 v[216:217], off
	v_lshl_add_u64 v[216:217], s[48:49], 0, v[208:209]
	s_mov_b32 m0, s51
	s_nop 0
	global_load_lds_dwordx4 v[216:217], off
	v_lshl_add_u64 v[216:217], s[48:49], 0, v[204:205]
	s_add_i32 m0, s51, 0x2000
	s_nop 0
	global_load_lds_dwordx4 v[216:217], off
	v_lshl_add_u64 v[216:217], v[240:241], 0, s[16:17]
	s_mov_b32 m0, s63
	s_nop 0
	global_load_lds_dwordx4 v[216:217], off
	v_lshl_add_u64 v[216:217], v[242:243], 0, s[16:17]
	s_mov_b32 m0, s64
	s_nop 0
	global_load_lds_dwordx4 v[216:217], off
	s_waitcnt vmcnt(8)
	s_waitcnt lgkmcnt(0)
	s_setprio 1
	s_barrier
	v_mfma_f32_16x16x32_bf16 v[62:65], v[106:109], v[162:165], v[62:65]
	v_mfma_f32_16x16x32_bf16 v[58:61], v[126:129], v[162:165], v[58:61]
	v_mfma_f32_16x16x32_bf16 v[46:49], v[106:109], v[170:173], v[46:49]
	v_mfma_f32_16x16x32_bf16 v[42:45], v[126:129], v[170:173], v[42:45]
	v_mfma_f32_16x16x32_bf16 v[30:33], v[106:109], v[178:181], v[30:33]
	v_mfma_f32_16x16x32_bf16 v[26:29], v[126:129], v[178:181], v[26:29]
	v_mfma_f32_16x16x32_bf16 v[14:17], v[106:109], v[222:225], v[14:17]
	v_mfma_f32_16x16x32_bf16 v[10:13], v[126:129], v[222:225], v[10:13]
	v_mfma_f32_16x16x32_bf16 v[62:65], v[110:113], v[166:169], v[62:65]
	v_mfma_f32_16x16x32_bf16 v[58:61], v[134:137], v[166:169], v[58:61]
	v_mfma_f32_16x16x32_bf16 v[46:49], v[110:113], v[174:177], v[46:49]
	v_mfma_f32_16x16x32_bf16 v[42:45], v[134:137], v[174:177], v[42:45]
	v_mfma_f32_16x16x32_bf16 v[30:33], v[110:113], v[182:185], v[30:33]
	v_mfma_f32_16x16x32_bf16 v[26:29], v[134:137], v[182:185], v[26:29]
	v_mfma_f32_16x16x32_bf16 v[14:17], v[110:113], v[226:229], v[14:17]
	v_mfma_f32_16x16x32_bf16 v[10:13], v[134:137], v[226:229], v[10:13]
	v_mfma_f32_16x16x32_bf16 v[54:57], v[146:149], v[162:165], v[54:57]
	v_mfma_f32_16x16x32_bf16 v[50:53], v[154:157], v[162:165], v[50:53]
	v_mfma_f32_16x16x32_bf16 v[38:41], v[146:149], v[170:173], v[38:41]
	v_mfma_f32_16x16x32_bf16 v[34:37], v[154:157], v[170:173], v[34:37]
	v_mfma_f32_16x16x32_bf16 v[22:25], v[146:149], v[178:181], v[22:25]
	v_mfma_f32_16x16x32_bf16 v[18:21], v[154:157], v[178:181], v[18:21]
	v_mfma_f32_16x16x32_bf16 v[6:9], v[146:149], v[222:225], v[6:9]
	v_mfma_f32_16x16x32_bf16 v[2:5], v[154:157], v[222:225], v[2:5]
	v_mfma_f32_16x16x32_bf16 v[54:57], v[150:153], v[166:169], v[54:57]
	v_mfma_f32_16x16x32_bf16 v[50:53], v[158:161], v[166:169], v[50:53]
	v_mfma_f32_16x16x32_bf16 v[38:41], v[150:153], v[174:177], v[38:41]
	v_mfma_f32_16x16x32_bf16 v[34:37], v[158:161], v[174:177], v[34:37]
	v_mfma_f32_16x16x32_bf16 v[22:25], v[150:153], v[182:185], v[22:25]
	v_mfma_f32_16x16x32_bf16 v[18:21], v[158:161], v[182:185], v[18:21]
	v_mfma_f32_16x16x32_bf16 v[6:9], v[150:153], v[226:229], v[6:9]
	v_mfma_f32_16x16x32_bf16 v[2:5], v[158:161], v[226:229], v[2:5]
	s_barrier
	s_setprio 0
	s_add_i32 s19, s19, 2
	s_add_u32 s7, s7, 0x100
	s_addc_u32 s18, s18, 0
	s_cmp_gt_u32 s19, 41
	s_mov_b64 s[48:49], s[0:1]
	.p2align 6

.Lrb2_skip:
	s_add_u32 s54, s52, 0xfffc0080
	s_addc_u32 s55, s53, -1
	s_add_i32 s67, 0, 0x10000
	s_cmp_eq_u32 s66, 12
	s_cselect_b32 s57, s19, s55
	s_cselect_b32 s56, s45, s54
	v_add_u32_e32 v0, s67, v158
	s_cselect_b32 s55, s41, s65
	s_cselect_b32 s54, s51, s64
	s_add_i32 s70, 0, 0x14000
	ds_read_b128 v[142:145], v0
	ds_read_b128 v[146:149], v0 offset:1024
	ds_read_b128 v[150:153], v0 offset:2048
	ds_read_b128 v[160:163], v0 offset:3072
	v_add_u32_e32 v0, s70, v158
	ds_read_b128 v[164:167], v0
	ds_read_b128 v[168:171], v0 offset:1024
	ds_read_b128 v[172:175], v0 offset:2048
	ds_read_b128 v[176:179], v0 offset:3072
	s_add_i32 m0, s59, 0xc000
	ds_read_b128 v[180:183], v159
	ds_read_b128 v[204:207], v159 offset:1024
	ds_read_b128 v[208:211], v159 offset:2048
	ds_read_b128 v[212:215], v159 offset:3072
	ds_read_b128 v[216:219], v159 offset:4096
	ds_read_b128 v[220:223], v159 offset:5120
	ds_read_b128 v[224:227], v159 offset:6144
	ds_read_b128 v[228:231], v159 offset:7168
	global_load_lds_dwordx4 v138, s[52:53]
	s_add_i32 m0, s59, 0xe000
	s_nop 0
	global_load_lds_dwordx4 v140, s[52:53]
	s_waitcnt vmcnt(8)
	s_waitcnt lgkmcnt(0)
	s_setprio 1
	s_barrier
	v_mfma_f32_16x16x32_bf16 v[126:129], v[142:145], v[180:183], 0
	v_mfma_f32_16x16x32_bf16 v[122:125], v[150:153], v[180:183], 0
	v_mfma_f32_16x16x32_bf16 v[110:113], v[142:145], v[208:211], 0
	v_mfma_f32_16x16x32_bf16 v[106:109], v[150:153], v[208:211], 0
	v_mfma_f32_16x16x32_bf16 v[94:97], v[142:145], v[216:219], 0
	v_mfma_f32_16x16x32_bf16 v[90:93], v[150:153], v[216:219], 0
	v_mfma_f32_16x16x32_bf16 v[78:81], v[142:145], v[224:227], 0
	v_mfma_f32_16x16x32_bf16 v[74:77], v[150:153], v[224:227], 0
	v_mfma_f32_16x16x32_bf16 v[126:129], v[146:149], v[204:207], v[126:129]
	v_mfma_f32_16x16x32_bf16 v[122:125], v[160:163], v[204:207], v[122:125]
	v_mfma_f32_16x16x32_bf16 v[110:113], v[146:149], v[212:215], v[110:113]
	v_mfma_f32_16x16x32_bf16 v[106:109], v[160:163], v[212:215], v[106:109]
	v_mfma_f32_16x16x32_bf16 v[94:97], v[146:149], v[220:223], v[94:97]
	v_mfma_f32_16x16x32_bf16 v[90:93], v[160:163], v[220:223], v[90:93]
	v_mfma_f32_16x16x32_bf16 v[78:81], v[146:149], v[228:231], v[78:81]
	v_mfma_f32_16x16x32_bf16 v[74:77], v[160:163], v[228:231], v[74:77]
	v_mfma_f32_16x16x32_bf16 v[118:121], v[164:167], v[180:183], 0
	v_mfma_f32_16x16x32_bf16 v[114:117], v[172:175], v[180:183], 0
	v_mfma_f32_16x16x32_bf16 v[102:105], v[164:167], v[208:211], 0
	v_mfma_f32_16x16x32_bf16 v[98:101], v[172:175], v[208:211], 0
	v_mfma_f32_16x16x32_bf16 v[86:89], v[164:167], v[216:219], 0
	v_mfma_f32_16x16x32_bf16 v[82:85], v[172:175], v[216:219], 0
	v_mfma_f32_16x16x32_bf16 v[70:73], v[164:167], v[224:227], 0
	v_mfma_f32_16x16x32_bf16 v[66:69], v[172:175], v[224:227], 0
	v_mfma_f32_16x16x32_bf16 v[118:121], v[168:171], v[204:207], v[118:121]
	v_mfma_f32_16x16x32_bf16 v[114:117], v[176:179], v[204:207], v[114:117]
	v_mfma_f32_16x16x32_bf16 v[102:105], v[168:171], v[212:215], v[102:105]
	v_mfma_f32_16x16x32_bf16 v[98:101], v[176:179], v[212:215], v[98:101]
	v_mfma_f32_16x16x32_bf16 v[86:89], v[168:171], v[220:223], v[86:89]
	v_mfma_f32_16x16x32_bf16 v[82:85], v[176:179], v[220:223], v[82:85]
	v_mfma_f32_16x16x32_bf16 v[70:73], v[168:171], v[228:231], v[70:73]
	v_mfma_f32_16x16x32_bf16 v[66:69], v[176:179], v[228:231], v[66:69]
	s_barrier
	s_setprio 0
	s_add_i32 s67, s67, s58
	s_mov_b32 m0, s67
	ds_read_b128 v[180:183], v159 offset:16384
	ds_read_b128 v[204:207], v159 offset:17408
	ds_read_b128 v[208:211], v159 offset:18432
	ds_read_b128 v[212:215], v159 offset:19456
	ds_read_b128 v[216:219], v159 offset:20480
	ds_read_b128 v[220:223], v159 offset:21504
	ds_read_b128 v[224:227], v159 offset:22528
	ds_read_b128 v[228:231], v159 offset:23552
	global_load_lds_dwordx4 v134, s[54:55]
	s_add_i32 m0, s67, 0x2000
	s_add_u32 s68, s54, 0x40000
	s_addc_u32 s69, s55, 0
	s_add_i32 s67, s70, s58
	global_load_lds_dwordx4 v130, s[54:55]
	s_mov_b32 m0, s67
	s_nop 0
	global_load_lds_dwordx4 v134, s[68:69]
	s_add_i32 m0, s67, 0x2000
	s_nop 0
	global_load_lds_dwordx4 v130, s[68:69]
	s_mov_b32 m0, s59
	s_nop 0
	global_load_lds_dwordx4 v136, s[56:57]
	s_mov_b32 m0, s60
	s_nop 0
	global_load_lds_dwordx4 v132, s[56:57]
	s_waitcnt vmcnt(8)
	s_waitcnt lgkmcnt(0)
	s_setprio 1
	s_barrier
	v_mfma_f32_16x16x32_bf16 v[62:65], v[142:145], v[180:183], 0
	v_mfma_f32_16x16x32_bf16 v[58:61], v[150:153], v[180:183], 0
	v_mfma_f32_16x16x32_bf16 v[46:49], v[142:145], v[208:211], 0
	v_mfma_f32_16x16x32_bf16 v[42:45], v[150:153], v[208:211], 0
	v_mfma_f32_16x16x32_bf16 v[30:33], v[142:145], v[216:219], 0
	v_mfma_f32_16x16x32_bf16 v[26:29], v[150:153], v[216:219], 0
	v_mfma_f32_16x16x32_bf16 v[14:17], v[142:145], v[224:227], 0
	v_mfma_f32_16x16x32_bf16 v[10:13], v[150:153], v[224:227], 0
	v_mfma_f32_16x16x32_bf16 v[62:65], v[146:149], v[204:207], v[62:65]
	v_mfma_f32_16x16x32_bf16 v[58:61], v[160:163], v[204:207], v[58:61]
	v_mfma_f32_16x16x32_bf16 v[46:49], v[146:149], v[212:215], v[46:49]
	v_mfma_f32_16x16x32_bf16 v[42:45], v[160:163], v[212:215], v[42:45]
	v_mfma_f32_16x16x32_bf16 v[30:33], v[146:149], v[220:223], v[30:33]
	v_mfma_f32_16x16x32_bf16 v[26:29], v[160:163], v[220:223], v[26:29]
	v_mfma_f32_16x16x32_bf16 v[14:17], v[146:149], v[228:231], v[14:17]
	v_mfma_f32_16x16x32_bf16 v[10:13], v[160:163], v[228:231], v[10:13]
	v_mfma_f32_16x16x32_bf16 v[54:57], v[164:167], v[180:183], 0
	v_mfma_f32_16x16x32_bf16 v[50:53], v[172:175], v[180:183], 0
	v_mfma_f32_16x16x32_bf16 v[38:41], v[164:167], v[208:211], 0
	v_mfma_f32_16x16x32_bf16 v[34:37], v[172:175], v[208:211], 0
	v_mfma_f32_16x16x32_bf16 v[22:25], v[164:167], v[216:219], 0
	v_mfma_f32_16x16x32_bf16 v[18:21], v[172:175], v[216:219], 0
	v_mfma_f32_16x16x32_bf16 v[6:9], v[164:167], v[224:227], 0
	v_mfma_f32_16x16x32_bf16 v[2:5], v[172:175], v[224:227], 0
	v_mfma_f32_16x16x32_bf16 v[54:57], v[168:171], v[204:207], v[54:57]
	v_mfma_f32_16x16x32_bf16 v[50:53], v[176:179], v[204:207], v[50:53]
	v_mfma_f32_16x16x32_bf16 v[38:41], v[168:171], v[212:215], v[38:41]
	v_mfma_f32_16x16x32_bf16 v[34:37], v[176:179], v[212:215], v[34:37]
	v_mfma_f32_16x16x32_bf16 v[22:25], v[168:171], v[220:223], v[22:25]
	v_mfma_f32_16x16x32_bf16 v[18:21], v[176:179], v[220:223], v[18:21]
	v_mfma_f32_16x16x32_bf16 v[6:9], v[168:171], v[228:231], v[6:9]
	v_mfma_f32_16x16x32_bf16 v[2:5], v[176:179], v[228:231], v[2:5]
	s_barrier
	s_setprio 0
	s_add_i32 s67, 0, 0x18000
	v_add_u32_e32 v0, s67, v158
	s_add_i32 s68, 0, 0x1c000
	ds_read_b128 v[142:145], v0
	ds_read_b128 v[146:149], v0 offset:1024
	ds_read_b128 v[150:153], v0 offset:2048
	ds_read_b128 v[160:163], v0 offset:3072
	v_add_u32_e32 v0, s68, v158
	ds_read_b128 v[164:167], v0
	ds_read_b128 v[168:171], v0 offset:1024
	ds_read_b128 v[172:175], v0 offset:2048
	ds_read_b128 v[176:179], v0 offset:3072
	s_add_u32 s56, s56, 0x40000
	s_addc_u32 s57, s57, 0
	s_mov_b32 m0, s61
	ds_read_b128 v[180:183], v159 offset:32768
	ds_read_b128 v[204:207], v159 offset:33792
	ds_read_b128 v[208:211], v159 offset:34816
	ds_read_b128 v[212:215], v159 offset:35840
	ds_read_b128 v[216:219], v159 offset:36864
	ds_read_b128 v[220:223], v159 offset:37888
	ds_read_b128 v[224:227], v159 offset:38912
	ds_read_b128 v[228:231], v159 offset:39936
	global_load_lds_dwordx4 v136, s[56:57]
	s_mov_b32 m0, s62
	s_nop 0
	global_load_lds_dwordx4 v132, s[56:57]
	s_waitcnt vmcnt(8)
	s_waitcnt lgkmcnt(0)
	s_setprio 1
	s_barrier
	v_mfma_f32_16x16x32_bf16 v[126:129], v[142:145], v[180:183], v[126:129]
	v_mfma_f32_16x16x32_bf16 v[122:125], v[150:153], v[180:183], v[122:125]
	v_mfma_f32_16x16x32_bf16 v[110:113], v[142:145], v[208:211], v[110:113]
	v_mfma_f32_16x16x32_bf16 v[106:109], v[150:153], v[208:211], v[106:109]
	v_mfma_f32_16x16x32_bf16 v[94:97], v[142:145], v[216:219], v[94:97]
	v_mfma_f32_16x16x32_bf16 v[90:93], v[150:153], v[216:219], v[90:93]
	v_mfma_f32_16x16x32_bf16 v[78:81], v[142:145], v[224:227], v[78:81]
	v_mfma_f32_16x16x32_bf16 v[74:77], v[150:153], v[224:227], v[74:77]
	v_mfma_f32_16x16x32_bf16 v[126:129], v[146:149], v[204:207], v[126:129]
	v_mfma_f32_16x16x32_bf16 v[122:125], v[160:163], v[204:207], v[122:125]
	v_mfma_f32_16x16x32_bf16 v[110:113], v[146:149], v[212:215], v[110:113]
	v_mfma_f32_16x16x32_bf16 v[106:109], v[160:163], v[212:215], v[106:109]
	v_mfma_f32_16x16x32_bf16 v[94:97], v[146:149], v[220:223], v[94:97]
	v_mfma_f32_16x16x32_bf16 v[90:93], v[160:163], v[220:223], v[90:93]
	v_mfma_f32_16x16x32_bf16 v[78:81], v[146:149], v[228:231], v[78:81]
	v_mfma_f32_16x16x32_bf16 v[74:77], v[160:163], v[228:231], v[74:77]
	v_mfma_f32_16x16x32_bf16 v[118:121], v[164:167], v[180:183], v[118:121]
	v_mfma_f32_16x16x32_bf16 v[114:117], v[172:175], v[180:183], v[114:117]
	v_mfma_f32_16x16x32_bf16 v[102:105], v[164:167], v[208:211], v[102:105]
	v_mfma_f32_16x16x32_bf16 v[98:101], v[172:175], v[208:211], v[98:101]
	v_mfma_f32_16x16x32_bf16 v[86:89], v[164:167], v[216:219], v[86:89]
	v_mfma_f32_16x16x32_bf16 v[82:85], v[172:175], v[216:219], v[82:85]
	v_mfma_f32_16x16x32_bf16 v[70:73], v[164:167], v[224:227], v[70:73]
	v_mfma_f32_16x16x32_bf16 v[66:69], v[172:175], v[224:227], v[66:69]
	v_mfma_f32_16x16x32_bf16 v[118:121], v[168:171], v[204:207], v[118:121]
	v_mfma_f32_16x16x32_bf16 v[114:117], v[176:179], v[204:207], v[114:117]
	v_mfma_f32_16x16x32_bf16 v[102:105], v[168:171], v[212:215], v[102:105]
	v_mfma_f32_16x16x32_bf16 v[98:101], v[176:179], v[212:215], v[98:101]
	v_mfma_f32_16x16x32_bf16 v[86:89], v[168:171], v[220:223], v[86:89]
	v_mfma_f32_16x16x32_bf16 v[82:85], v[176:179], v[220:223], v[82:85]
	v_mfma_f32_16x16x32_bf16 v[70:73], v[168:171], v[228:231], v[70:73]
	v_mfma_f32_16x16x32_bf16 v[66:69], v[176:179], v[228:231], v[66:69]
	s_barrier
	s_setprio 0
	s_add_i32 s69, s67, s58
	s_add_u32 s54, s54, 0x80
	s_addc_u32 s55, s55, 0
	s_mov_b32 m0, s69
	ds_read_b128 v[180:183], v159 offset:49152
	ds_read_b128 v[204:207], v159 offset:50176
	ds_read_b128 v[208:211], v159 offset:51200
	ds_read_b128 v[212:215], v159 offset:52224
	ds_read_b128 v[216:219], v159 offset:53248
	ds_read_b128 v[220:223], v159 offset:54272
	ds_read_b128 v[224:227], v159 offset:55296
	ds_read_b128 v[228:231], v159 offset:56320
	global_load_lds_dwordx4 v134, s[54:55]
	s_add_i32 m0, s69, 0x2000
	s_add_i32 s69, s68, s58
	global_load_lds_dwordx4 v130, s[54:55]
	s_add_u32 s54, s54, 0x40000
	s_addc_u32 s55, s55, 0
	s_mov_b32 m0, s69
	s_sub_u32 s56, s56, 0x3ff80
	global_load_lds_dwordx4 v134, s[54:55]
	s_subb_u32 s57, s57, 0
	s_add_i32 m0, s69, 0x2000
	s_nop 0
	global_load_lds_dwordx4 v130, s[54:55]
	s_mov_b32 m0, s5
	s_nop 0
	global_load_lds_dwordx4 v136, s[56:57]
	s_mov_b32 m0, s6
	s_nop 0
	global_load_lds_dwordx4 v132, s[56:57]
	s_waitcnt vmcnt(8)
	s_waitcnt lgkmcnt(0)
	s_setprio 1
	s_barrier
	v_mfma_f32_16x16x32_bf16 v[62:65], v[142:145], v[180:183], v[62:65]
	v_mfma_f32_16x16x32_bf16 v[58:61], v[150:153], v[180:183], v[58:61]
	v_mfma_f32_16x16x32_bf16 v[46:49], v[142:145], v[208:211], v[46:49]
	v_mfma_f32_16x16x32_bf16 v[42:45], v[150:153], v[208:211], v[42:45]
	v_mfma_f32_16x16x32_bf16 v[30:33], v[142:145], v[216:219], v[30:33]
	v_mfma_f32_16x16x32_bf16 v[26:29], v[150:153], v[216:219], v[26:29]
	v_mfma_f32_16x16x32_bf16 v[14:17], v[142:145], v[224:227], v[14:17]
	v_mfma_f32_16x16x32_bf16 v[10:13], v[150:153], v[224:227], v[10:13]
	v_mfma_f32_16x16x32_bf16 v[62:65], v[146:149], v[204:207], v[62:65]
	v_mfma_f32_16x16x32_bf16 v[58:61], v[160:163], v[204:207], v[58:61]
	v_mfma_f32_16x16x32_bf16 v[46:49], v[146:149], v[212:215], v[46:49]
	v_mfma_f32_16x16x32_bf16 v[42:45], v[160:163], v[212:215], v[42:45]
	v_mfma_f32_16x16x32_bf16 v[30:33], v[146:149], v[220:223], v[30:33]
	v_mfma_f32_16x16x32_bf16 v[26:29], v[160:163], v[220:223], v[26:29]
	v_mfma_f32_16x16x32_bf16 v[14:17], v[146:149], v[228:231], v[14:17]
	v_mfma_f32_16x16x32_bf16 v[10:13], v[160:163], v[228:231], v[10:13]
	v_mfma_f32_16x16x32_bf16 v[54:57], v[164:167], v[180:183], v[54:57]
	v_mfma_f32_16x16x32_bf16 v[50:53], v[172:175], v[180:183], v[50:53]
	v_mfma_f32_16x16x32_bf16 v[38:41], v[164:167], v[208:211], v[38:41]
	v_mfma_f32_16x16x32_bf16 v[34:37], v[172:175], v[208:211], v[34:37]
	v_mfma_f32_16x16x32_bf16 v[22:25], v[164:167], v[216:219], v[22:25]
	v_mfma_f32_16x16x32_bf16 v[18:21], v[172:175], v[216:219], v[18:21]
	v_mfma_f32_16x16x32_bf16 v[6:9], v[164:167], v[224:227], v[6:9]
	v_mfma_f32_16x16x32_bf16 v[2:5], v[172:175], v[224:227], v[2:5]
	v_mfma_f32_16x16x32_bf16 v[54:57], v[168:171], v[204:207], v[54:57]
	v_mfma_f32_16x16x32_bf16 v[50:53], v[176:179], v[204:207], v[50:53]
	v_mfma_f32_16x16x32_bf16 v[38:41], v[168:171], v[212:215], v[38:41]
	v_mfma_f32_16x16x32_bf16 v[34:37], v[176:179], v[212:215], v[34:37]
	v_mfma_f32_16x16x32_bf16 v[22:25], v[168:171], v[220:223], v[22:25]
	v_mfma_f32_16x16x32_bf16 v[18:21], v[176:179], v[220:223], v[18:21]
	v_mfma_f32_16x16x32_bf16 v[6:9], v[168:171], v[228:231], v[6:9]
	v_mfma_f32_16x16x32_bf16 v[2:5], v[176:179], v[228:231], v[2:5]
	s_barrier
	s_setprio 0
	s_add_i32 s66, s66, 2
	s_add_u32 s52, s52, 0x100
	s_addc_u32 s53, s53, 0
	s_add_u32 s64, s64, 0x100
	s_addc_u32 s65, s65, 0
	s_cmp_gt_u32 s66, 13
	.p2align 6

.Lrb3_skip:
	s_add_u32 s54, s52, 0xfffc0080
	s_addc_u32 s55, s53, -1
	s_add_i32 s61, 0, 0x10000
	s_cmp_eq_u32 s60, 12
	s_cselect_b32 s57, s19, s55
	s_cselect_b32 s56, s45, s54
	v_add_u32_e32 v0, s61, v160
	s_cselect_b32 s55, s41, s59
	s_cselect_b32 s54, s47, s58
	s_add_i32 s64, 0, 0x14000
	ds_read_b128 v[142:145], v0
	ds_read_b128 v[146:149], v0 offset:1024
	ds_read_b128 v[150:153], v0 offset:2048
	ds_read_b128 v[154:157], v0 offset:3072
	v_add_u32_e32 v0, s64, v160
	ds_read_b128 v[162:165], v0
	ds_read_b128 v[166:169], v0 offset:1024
	ds_read_b128 v[170:173], v0 offset:2048
	ds_read_b128 v[174:177], v0 offset:3072
	s_add_i32 m0, s71, 0xc000
	ds_read_b128 v[178:181], v161
	ds_read_b128 v[182:185], v161 offset:1024
	ds_read_b128 v[204:207], v161 offset:2048
	ds_read_b128 v[208:211], v161 offset:3072
	ds_read_b128 v[212:215], v161 offset:4096
	ds_read_b128 v[216:219], v161 offset:5120
	ds_read_b128 v[220:223], v161 offset:6144
	ds_read_b128 v[224:227], v161 offset:7168
	global_load_lds_dwordx4 v138, s[52:53]
	s_add_i32 m0, s71, 0xe000
	s_nop 0
	global_load_lds_dwordx4 v140, s[52:53]
	s_waitcnt vmcnt(8)
	s_waitcnt lgkmcnt(0)
	s_setprio 1
	s_barrier
	v_mfma_f32_16x16x32_bf16 v[126:129], v[142:145], v[178:181], 0
	v_mfma_f32_16x16x32_bf16 v[122:125], v[150:153], v[178:181], 0
	v_mfma_f32_16x16x32_bf16 v[110:113], v[142:145], v[204:207], 0
	v_mfma_f32_16x16x32_bf16 v[106:109], v[150:153], v[204:207], 0
	v_mfma_f32_16x16x32_bf16 v[94:97], v[142:145], v[212:215], 0
	v_mfma_f32_16x16x32_bf16 v[90:93], v[150:153], v[212:215], 0
	v_mfma_f32_16x16x32_bf16 v[78:81], v[142:145], v[220:223], 0
	v_mfma_f32_16x16x32_bf16 v[74:77], v[150:153], v[220:223], 0
	v_mfma_f32_16x16x32_bf16 v[126:129], v[146:149], v[182:185], v[126:129]
	v_mfma_f32_16x16x32_bf16 v[122:125], v[154:157], v[182:185], v[122:125]
	v_mfma_f32_16x16x32_bf16 v[110:113], v[146:149], v[208:211], v[110:113]
	v_mfma_f32_16x16x32_bf16 v[106:109], v[154:157], v[208:211], v[106:109]
	v_mfma_f32_16x16x32_bf16 v[94:97], v[146:149], v[216:219], v[94:97]
	v_mfma_f32_16x16x32_bf16 v[90:93], v[154:157], v[216:219], v[90:93]
	v_mfma_f32_16x16x32_bf16 v[78:81], v[146:149], v[224:227], v[78:81]
	v_mfma_f32_16x16x32_bf16 v[74:77], v[154:157], v[224:227], v[74:77]
	v_mfma_f32_16x16x32_bf16 v[118:121], v[162:165], v[178:181], 0
	v_mfma_f32_16x16x32_bf16 v[114:117], v[170:173], v[178:181], 0
	v_mfma_f32_16x16x32_bf16 v[102:105], v[162:165], v[204:207], 0
	v_mfma_f32_16x16x32_bf16 v[98:101], v[170:173], v[204:207], 0
	v_mfma_f32_16x16x32_bf16 v[86:89], v[162:165], v[212:215], 0
	v_mfma_f32_16x16x32_bf16 v[82:85], v[170:173], v[212:215], 0
	v_mfma_f32_16x16x32_bf16 v[70:73], v[162:165], v[220:223], 0
	v_mfma_f32_16x16x32_bf16 v[66:69], v[170:173], v[220:223], 0
	v_mfma_f32_16x16x32_bf16 v[118:121], v[166:169], v[182:185], v[118:121]
	v_mfma_f32_16x16x32_bf16 v[114:117], v[174:177], v[182:185], v[114:117]
	v_mfma_f32_16x16x32_bf16 v[102:105], v[166:169], v[208:211], v[102:105]
	v_mfma_f32_16x16x32_bf16 v[98:101], v[174:177], v[208:211], v[98:101]
	v_mfma_f32_16x16x32_bf16 v[86:89], v[166:169], v[216:219], v[86:89]
	v_mfma_f32_16x16x32_bf16 v[82:85], v[174:177], v[216:219], v[82:85]
	v_mfma_f32_16x16x32_bf16 v[70:73], v[166:169], v[224:227], v[70:73]
	v_mfma_f32_16x16x32_bf16 v[66:69], v[174:177], v[224:227], v[66:69]
	s_barrier
	s_setprio 0
	s_add_i32 s61, s61, s70
	s_mov_b32 m0, s61
	ds_read_b128 v[178:181], v161 offset:16384
	ds_read_b128 v[182:185], v161 offset:17408
	ds_read_b128 v[204:207], v161 offset:18432
	ds_read_b128 v[208:211], v161 offset:19456
	ds_read_b128 v[212:215], v161 offset:20480
	ds_read_b128 v[216:219], v161 offset:21504
	ds_read_b128 v[220:223], v161 offset:22528
	ds_read_b128 v[224:227], v161 offset:23552
	global_load_lds_dwordx4 v134, s[54:55]
	s_add_i32 m0, s61, 0x2000
	s_add_u32 s62, s54, 0x40000
	s_addc_u32 s63, s55, 0
	s_add_i32 s61, s64, s70
	global_load_lds_dwordx4 v130, s[54:55]
	s_mov_b32 m0, s61
	s_nop 0
	global_load_lds_dwordx4 v134, s[62:63]
	s_add_i32 m0, s61, 0x2000
	s_nop 0
	global_load_lds_dwordx4 v130, s[62:63]
	s_mov_b32 m0, s71
	s_nop 0
	global_load_lds_dwordx4 v136, s[56:57]
	s_mov_b32 m0, s72
	s_nop 0
	global_load_lds_dwordx4 v132, s[56:57]
	s_waitcnt vmcnt(8)
	s_waitcnt lgkmcnt(0)
	s_setprio 1
	s_barrier
	v_mfma_f32_16x16x32_bf16 v[62:65], v[142:145], v[178:181], 0
	v_mfma_f32_16x16x32_bf16 v[58:61], v[150:153], v[178:181], 0
	v_mfma_f32_16x16x32_bf16 v[46:49], v[142:145], v[204:207], 0
	v_mfma_f32_16x16x32_bf16 v[42:45], v[150:153], v[204:207], 0
	v_mfma_f32_16x16x32_bf16 v[30:33], v[142:145], v[212:215], 0
	v_mfma_f32_16x16x32_bf16 v[26:29], v[150:153], v[212:215], 0
	v_mfma_f32_16x16x32_bf16 v[14:17], v[142:145], v[220:223], 0
	v_mfma_f32_16x16x32_bf16 v[10:13], v[150:153], v[220:223], 0
	v_mfma_f32_16x16x32_bf16 v[62:65], v[146:149], v[182:185], v[62:65]
	v_mfma_f32_16x16x32_bf16 v[58:61], v[154:157], v[182:185], v[58:61]
	v_mfma_f32_16x16x32_bf16 v[46:49], v[146:149], v[208:211], v[46:49]
	v_mfma_f32_16x16x32_bf16 v[42:45], v[154:157], v[208:211], v[42:45]
	v_mfma_f32_16x16x32_bf16 v[30:33], v[146:149], v[216:219], v[30:33]
	v_mfma_f32_16x16x32_bf16 v[26:29], v[154:157], v[216:219], v[26:29]
	v_mfma_f32_16x16x32_bf16 v[14:17], v[146:149], v[224:227], v[14:17]
	v_mfma_f32_16x16x32_bf16 v[10:13], v[154:157], v[224:227], v[10:13]
	v_mfma_f32_16x16x32_bf16 v[54:57], v[162:165], v[178:181], 0
	v_mfma_f32_16x16x32_bf16 v[50:53], v[170:173], v[178:181], 0
	v_mfma_f32_16x16x32_bf16 v[38:41], v[162:165], v[204:207], 0
	v_mfma_f32_16x16x32_bf16 v[34:37], v[170:173], v[204:207], 0
	v_mfma_f32_16x16x32_bf16 v[22:25], v[162:165], v[212:215], 0
	v_mfma_f32_16x16x32_bf16 v[18:21], v[170:173], v[212:215], 0
	v_mfma_f32_16x16x32_bf16 v[6:9], v[162:165], v[220:223], 0
	v_mfma_f32_16x16x32_bf16 v[2:5], v[170:173], v[220:223], 0
	v_mfma_f32_16x16x32_bf16 v[54:57], v[166:169], v[182:185], v[54:57]
	v_mfma_f32_16x16x32_bf16 v[50:53], v[174:177], v[182:185], v[50:53]
	v_mfma_f32_16x16x32_bf16 v[38:41], v[166:169], v[208:211], v[38:41]
	v_mfma_f32_16x16x32_bf16 v[34:37], v[174:177], v[208:211], v[34:37]
	v_mfma_f32_16x16x32_bf16 v[22:25], v[166:169], v[216:219], v[22:25]
	v_mfma_f32_16x16x32_bf16 v[18:21], v[174:177], v[216:219], v[18:21]
	v_mfma_f32_16x16x32_bf16 v[6:9], v[166:169], v[224:227], v[6:9]
	v_mfma_f32_16x16x32_bf16 v[2:5], v[174:177], v[224:227], v[2:5]
	s_barrier
	s_setprio 0
	s_add_i32 s61, 0, 0x18000
	v_add_u32_e32 v0, s61, v160
	s_add_i32 s62, 0, 0x1c000
	ds_read_b128 v[142:145], v0
	ds_read_b128 v[146:149], v0 offset:1024
	ds_read_b128 v[150:153], v0 offset:2048
	ds_read_b128 v[154:157], v0 offset:3072
	v_add_u32_e32 v0, s62, v160
	ds_read_b128 v[162:165], v0
	ds_read_b128 v[166:169], v0 offset:1024
	ds_read_b128 v[170:173], v0 offset:2048
	ds_read_b128 v[174:177], v0 offset:3072
	s_add_u32 s56, s56, 0x40000
	s_addc_u32 s57, s57, 0
	s_mov_b32 m0, s73
	ds_read_b128 v[178:181], v161 offset:32768
	ds_read_b128 v[182:185], v161 offset:33792
	ds_read_b128 v[204:207], v161 offset:34816
	ds_read_b128 v[208:211], v161 offset:35840
	ds_read_b128 v[212:215], v161 offset:36864
	ds_read_b128 v[216:219], v161 offset:37888
	ds_read_b128 v[220:223], v161 offset:38912
	ds_read_b128 v[224:227], v161 offset:39936
	global_load_lds_dwordx4 v136, s[56:57]
	s_mov_b32 m0, s74
	s_nop 0
	global_load_lds_dwordx4 v132, s[56:57]
	s_waitcnt vmcnt(8)
	s_waitcnt lgkmcnt(0)
	s_setprio 1
	s_barrier
	v_mfma_f32_16x16x32_bf16 v[126:129], v[142:145], v[178:181], v[126:129]
	v_mfma_f32_16x16x32_bf16 v[122:125], v[150:153], v[178:181], v[122:125]
	v_mfma_f32_16x16x32_bf16 v[110:113], v[142:145], v[204:207], v[110:113]
	v_mfma_f32_16x16x32_bf16 v[106:109], v[150:153], v[204:207], v[106:109]
	v_mfma_f32_16x16x32_bf16 v[94:97], v[142:145], v[212:215], v[94:97]
	v_mfma_f32_16x16x32_bf16 v[90:93], v[150:153], v[212:215], v[90:93]
	v_mfma_f32_16x16x32_bf16 v[78:81], v[142:145], v[220:223], v[78:81]
	v_mfma_f32_16x16x32_bf16 v[74:77], v[150:153], v[220:223], v[74:77]
	v_mfma_f32_16x16x32_bf16 v[126:129], v[146:149], v[182:185], v[126:129]
	v_mfma_f32_16x16x32_bf16 v[122:125], v[154:157], v[182:185], v[122:125]
	v_mfma_f32_16x16x32_bf16 v[110:113], v[146:149], v[208:211], v[110:113]
	v_mfma_f32_16x16x32_bf16 v[106:109], v[154:157], v[208:211], v[106:109]
	v_mfma_f32_16x16x32_bf16 v[94:97], v[146:149], v[216:219], v[94:97]
	v_mfma_f32_16x16x32_bf16 v[90:93], v[154:157], v[216:219], v[90:93]
	v_mfma_f32_16x16x32_bf16 v[78:81], v[146:149], v[224:227], v[78:81]
	v_mfma_f32_16x16x32_bf16 v[74:77], v[154:157], v[224:227], v[74:77]
	v_mfma_f32_16x16x32_bf16 v[118:121], v[162:165], v[178:181], v[118:121]
	v_mfma_f32_16x16x32_bf16 v[114:117], v[170:173], v[178:181], v[114:117]
	v_mfma_f32_16x16x32_bf16 v[102:105], v[162:165], v[204:207], v[102:105]
	v_mfma_f32_16x16x32_bf16 v[98:101], v[170:173], v[204:207], v[98:101]
	v_mfma_f32_16x16x32_bf16 v[86:89], v[162:165], v[212:215], v[86:89]
	v_mfma_f32_16x16x32_bf16 v[82:85], v[170:173], v[212:215], v[82:85]
	v_mfma_f32_16x16x32_bf16 v[70:73], v[162:165], v[220:223], v[70:73]
	v_mfma_f32_16x16x32_bf16 v[66:69], v[170:173], v[220:223], v[66:69]
	v_mfma_f32_16x16x32_bf16 v[118:121], v[166:169], v[182:185], v[118:121]
	v_mfma_f32_16x16x32_bf16 v[114:117], v[174:177], v[182:185], v[114:117]
	v_mfma_f32_16x16x32_bf16 v[102:105], v[166:169], v[208:211], v[102:105]
	v_mfma_f32_16x16x32_bf16 v[98:101], v[174:177], v[208:211], v[98:101]
	v_mfma_f32_16x16x32_bf16 v[86:89], v[166:169], v[216:219], v[86:89]
	v_mfma_f32_16x16x32_bf16 v[82:85], v[174:177], v[216:219], v[82:85]
	v_mfma_f32_16x16x32_bf16 v[70:73], v[166:169], v[224:227], v[70:73]
	v_mfma_f32_16x16x32_bf16 v[66:69], v[174:177], v[224:227], v[66:69]
	s_barrier
	s_setprio 0
	s_add_i32 s63, s61, s70
	s_add_u32 s54, s54, 0x80
	s_addc_u32 s55, s55, 0
	s_mov_b32 m0, s63
	ds_read_b128 v[178:181], v161 offset:49152
	ds_read_b128 v[182:185], v161 offset:50176
	ds_read_b128 v[204:207], v161 offset:51200
	ds_read_b128 v[208:211], v161 offset:52224
	ds_read_b128 v[212:215], v161 offset:53248
	ds_read_b128 v[216:219], v161 offset:54272
	ds_read_b128 v[220:223], v161 offset:55296
	ds_read_b128 v[224:227], v161 offset:56320
	global_load_lds_dwordx4 v134, s[54:55]
	s_add_i32 m0, s63, 0x2000
	s_add_i32 s63, s62, s70
	global_load_lds_dwordx4 v130, s[54:55]
	s_add_u32 s54, s54, 0x40000
	s_addc_u32 s55, s55, 0
	s_mov_b32 m0, s63
	s_sub_u32 s56, s56, 0x3ff80
	global_load_lds_dwordx4 v134, s[54:55]
	s_subb_u32 s57, s57, 0
	s_add_i32 m0, s63, 0x2000
	s_nop 0
	global_load_lds_dwordx4 v130, s[54:55]
	s_mov_b32 m0, s86
	s_nop 0
	global_load_lds_dwordx4 v136, s[56:57]
	s_mov_b32 m0, s87
	s_nop 0
	global_load_lds_dwordx4 v132, s[56:57]
	s_waitcnt vmcnt(8)
	s_waitcnt lgkmcnt(0)
	s_setprio 1
	s_barrier
	v_mfma_f32_16x16x32_bf16 v[62:65], v[142:145], v[178:181], v[62:65]
	v_mfma_f32_16x16x32_bf16 v[58:61], v[150:153], v[178:181], v[58:61]
	v_mfma_f32_16x16x32_bf16 v[46:49], v[142:145], v[204:207], v[46:49]
	v_mfma_f32_16x16x32_bf16 v[42:45], v[150:153], v[204:207], v[42:45]
	v_mfma_f32_16x16x32_bf16 v[30:33], v[142:145], v[212:215], v[30:33]
	v_mfma_f32_16x16x32_bf16 v[26:29], v[150:153], v[212:215], v[26:29]
	v_mfma_f32_16x16x32_bf16 v[14:17], v[142:145], v[220:223], v[14:17]
	v_mfma_f32_16x16x32_bf16 v[10:13], v[150:153], v[220:223], v[10:13]
	v_mfma_f32_16x16x32_bf16 v[62:65], v[146:149], v[182:185], v[62:65]
	v_mfma_f32_16x16x32_bf16 v[58:61], v[154:157], v[182:185], v[58:61]
	v_mfma_f32_16x16x32_bf16 v[46:49], v[146:149], v[208:211], v[46:49]
	v_mfma_f32_16x16x32_bf16 v[42:45], v[154:157], v[208:211], v[42:45]
	v_mfma_f32_16x16x32_bf16 v[30:33], v[146:149], v[216:219], v[30:33]
	v_mfma_f32_16x16x32_bf16 v[26:29], v[154:157], v[216:219], v[26:29]
	v_mfma_f32_16x16x32_bf16 v[14:17], v[146:149], v[224:227], v[14:17]
	v_mfma_f32_16x16x32_bf16 v[10:13], v[154:157], v[224:227], v[10:13]
	v_mfma_f32_16x16x32_bf16 v[54:57], v[162:165], v[178:181], v[54:57]
	v_mfma_f32_16x16x32_bf16 v[50:53], v[170:173], v[178:181], v[50:53]
	v_mfma_f32_16x16x32_bf16 v[38:41], v[162:165], v[204:207], v[38:41]
	v_mfma_f32_16x16x32_bf16 v[34:37], v[170:173], v[204:207], v[34:37]
	v_mfma_f32_16x16x32_bf16 v[22:25], v[162:165], v[212:215], v[22:25]
	v_mfma_f32_16x16x32_bf16 v[18:21], v[170:173], v[212:215], v[18:21]
	v_mfma_f32_16x16x32_bf16 v[6:9], v[162:165], v[220:223], v[6:9]
	v_mfma_f32_16x16x32_bf16 v[2:5], v[170:173], v[220:223], v[2:5]
	v_mfma_f32_16x16x32_bf16 v[54:57], v[166:169], v[182:185], v[54:57]
	v_mfma_f32_16x16x32_bf16 v[50:53], v[174:177], v[182:185], v[50:53]
	v_mfma_f32_16x16x32_bf16 v[38:41], v[166:169], v[208:211], v[38:41]
	v_mfma_f32_16x16x32_bf16 v[34:37], v[174:177], v[208:211], v[34:37]
	v_mfma_f32_16x16x32_bf16 v[22:25], v[166:169], v[216:219], v[22:25]
	v_mfma_f32_16x16x32_bf16 v[18:21], v[174:177], v[216:219], v[18:21]
	v_mfma_f32_16x16x32_bf16 v[6:9], v[166:169], v[224:227], v[6:9]
	v_mfma_f32_16x16x32_bf16 v[2:5], v[174:177], v[224:227], v[2:5]
	s_barrier
	s_setprio 0
	s_add_i32 s60, s60, 2
	s_add_u32 s52, s52, 0x100
	s_addc_u32 s53, s53, 0
	s_add_u32 s58, s58, 0x100
	s_addc_u32 s59, s59, 0
	s_cmp_gt_u32 s60, 13
	.p2align 6

.Lrb4_skip:
	s_add_u32 s47, s52, 0xfffc0080
	s_addc_u32 s54, s53, -1
	s_add_i32 s68, 0, 0x10000
	s_cmp_eq_u32 s45, 12
	s_cselect_b32 s57, s1, s54
	s_cselect_b32 s56, s5, s47
	v_add_u32_e32 v0, s68, v221
	s_cselect_b32 s55, s6, s19
	s_cselect_b32 s54, s7, s18
	s_add_i32 s47, 0, 0x14000
	ds_read_b128 v[106:109], v0
	ds_read_b128 v[110:113], v0 offset:1024
	ds_read_b128 v[126:129], v0 offset:2048
	ds_read_b128 v[134:137], v0 offset:3072
	v_add_u32_e32 v0, s47, v221
	ds_read_b128 v[146:149], v0
	ds_read_b128 v[150:153], v0 offset:1024
	ds_read_b128 v[154:157], v0 offset:2048
	ds_read_b128 v[158:161], v0 offset:3072
	v_lshl_add_u64 v[216:217], s[52:53], 0, v[212:213]
	s_add_i32 m0, s59, 0xc000
	ds_read_b128 v[162:165], v222
	ds_read_b128 v[166:169], v222 offset:1024
	ds_read_b128 v[170:173], v222 offset:2048
	ds_read_b128 v[174:177], v222 offset:3072
	ds_read_b128 v[178:181], v222 offset:4096
	ds_read_b128 v[182:185], v222 offset:5120
	ds_read_b128 v[224:227], v222 offset:6144
	ds_read_b128 v[228:231], v222 offset:7168
	global_load_lds_dwordx4 v[216:217], off
	v_lshl_add_u64 v[216:217], s[52:53], 0, v[214:215]
	s_add_i32 m0, s59, 0xe000
	s_nop 0
	global_load_lds_dwordx4 v[216:217], off
	s_waitcnt vmcnt(8)
	s_waitcnt lgkmcnt(0)
	s_setprio 1
	s_barrier
	v_mfma_f32_16x16x32_bf16 v[142:145], v[106:109], v[162:165], 0
	v_mfma_f32_16x16x32_bf16 v[138:141], v[126:129], v[162:165], 0
	v_mfma_f32_16x16x32_bf16 v[118:121], v[106:109], v[170:173], 0
	v_mfma_f32_16x16x32_bf16 v[114:117], v[126:129], v[170:173], 0
	v_mfma_f32_16x16x32_bf16 v[94:97], v[106:109], v[178:181], 0
	v_mfma_f32_16x16x32_bf16 v[90:93], v[126:129], v[178:181], 0
	v_mfma_f32_16x16x32_bf16 v[78:81], v[106:109], v[224:227], 0
	v_mfma_f32_16x16x32_bf16 v[74:77], v[126:129], v[224:227], 0
	v_mfma_f32_16x16x32_bf16 v[142:145], v[110:113], v[166:169], v[142:145]
	v_mfma_f32_16x16x32_bf16 v[138:141], v[134:137], v[166:169], v[138:141]
	v_mfma_f32_16x16x32_bf16 v[118:121], v[110:113], v[174:177], v[118:121]
	v_mfma_f32_16x16x32_bf16 v[114:117], v[134:137], v[174:177], v[114:117]
	v_mfma_f32_16x16x32_bf16 v[94:97], v[110:113], v[182:185], v[94:97]
	v_mfma_f32_16x16x32_bf16 v[90:93], v[134:137], v[182:185], v[90:93]
	v_mfma_f32_16x16x32_bf16 v[78:81], v[110:113], v[228:231], v[78:81]
	v_mfma_f32_16x16x32_bf16 v[74:77], v[134:137], v[228:231], v[74:77]
	v_mfma_f32_16x16x32_bf16 v[130:133], v[146:149], v[162:165], 0
	v_mfma_f32_16x16x32_bf16 v[122:125], v[154:157], v[162:165], 0
	v_mfma_f32_16x16x32_bf16 v[102:105], v[146:149], v[170:173], 0
	v_mfma_f32_16x16x32_bf16 v[98:101], v[154:157], v[170:173], 0
	v_mfma_f32_16x16x32_bf16 v[86:89], v[146:149], v[178:181], 0
	v_mfma_f32_16x16x32_bf16 v[82:85], v[154:157], v[178:181], 0
	v_mfma_f32_16x16x32_bf16 v[70:73], v[146:149], v[224:227], 0
	v_mfma_f32_16x16x32_bf16 v[66:69], v[154:157], v[224:227], 0
	v_mfma_f32_16x16x32_bf16 v[130:133], v[150:153], v[166:169], v[130:133]
	v_mfma_f32_16x16x32_bf16 v[122:125], v[158:161], v[166:169], v[122:125]
	v_mfma_f32_16x16x32_bf16 v[102:105], v[150:153], v[174:177], v[102:105]
	v_mfma_f32_16x16x32_bf16 v[98:101], v[158:161], v[174:177], v[98:101]
	v_mfma_f32_16x16x32_bf16 v[86:89], v[150:153], v[182:185], v[86:89]
	v_mfma_f32_16x16x32_bf16 v[82:85], v[158:161], v[182:185], v[82:85]
	v_mfma_f32_16x16x32_bf16 v[70:73], v[150:153], v[228:231], v[70:73]
	v_mfma_f32_16x16x32_bf16 v[66:69], v[158:161], v[228:231], v[66:69]
	s_barrier
	s_setprio 0
	s_add_i32 s68, s68, s58
	v_lshl_add_u64 v[216:217], s[54:55], 0, v[208:209]
	s_mov_b32 m0, s68
	ds_read_b128 v[162:165], v222 offset:16384
	ds_read_b128 v[166:169], v222 offset:17408
	ds_read_b128 v[170:173], v222 offset:18432
	ds_read_b128 v[174:177], v222 offset:19456
	ds_read_b128 v[178:181], v222 offset:20480
	ds_read_b128 v[182:185], v222 offset:21504
	ds_read_b128 v[224:227], v222 offset:22528
	ds_read_b128 v[228:231], v222 offset:23552
	global_load_lds_dwordx4 v[216:217], off
	s_add_i32 m0, s68, 0x2000
	s_add_u32 s68, s54, 0x40000
	v_lshl_add_u64 v[240:241], s[54:55], 0, v[204:205]
	s_addc_u32 s69, s55, 0
	s_add_i32 s47, s47, s58
	global_load_lds_dwordx4 v[240:241], off
	v_lshl_add_u64 v[242:243], s[68:69], 0, v[208:209]
	s_mov_b32 m0, s47
	v_lshl_add_u64 v[244:245], s[56:57], 0, v[206:207]
	global_load_lds_dwordx4 v[242:243], off
	v_lshl_add_u64 v[242:243], s[68:69], 0, v[204:205]
	s_add_i32 m0, s47, 0x2000
	s_nop 0
	global_load_lds_dwordx4 v[242:243], off
	v_lshl_add_u64 v[242:243], s[56:57], 0, v[210:211]
	s_mov_b32 m0, s59
	s_nop 0
	global_load_lds_dwordx4 v[242:243], off
	s_mov_b32 m0, s60
	s_nop 0
	global_load_lds_dwordx4 v[244:245], off
	s_waitcnt vmcnt(8)
	s_waitcnt lgkmcnt(0)
	s_setprio 1
	s_barrier
	v_mfma_f32_16x16x32_bf16 v[62:65], v[106:109], v[162:165], 0
	v_mfma_f32_16x16x32_bf16 v[58:61], v[126:129], v[162:165], 0
	v_mfma_f32_16x16x32_bf16 v[46:49], v[106:109], v[170:173], 0
	v_mfma_f32_16x16x32_bf16 v[42:45], v[126:129], v[170:173], 0
	v_mfma_f32_16x16x32_bf16 v[30:33], v[106:109], v[178:181], 0
	v_mfma_f32_16x16x32_bf16 v[26:29], v[126:129], v[178:181], 0
	v_mfma_f32_16x16x32_bf16 v[14:17], v[106:109], v[224:227], 0
	v_mfma_f32_16x16x32_bf16 v[10:13], v[126:129], v[224:227], 0
	v_mfma_f32_16x16x32_bf16 v[62:65], v[110:113], v[166:169], v[62:65]
	v_mfma_f32_16x16x32_bf16 v[58:61], v[134:137], v[166:169], v[58:61]
	v_mfma_f32_16x16x32_bf16 v[46:49], v[110:113], v[174:177], v[46:49]
	v_mfma_f32_16x16x32_bf16 v[42:45], v[134:137], v[174:177], v[42:45]
	v_mfma_f32_16x16x32_bf16 v[30:33], v[110:113], v[182:185], v[30:33]
	v_mfma_f32_16x16x32_bf16 v[26:29], v[134:137], v[182:185], v[26:29]
	v_mfma_f32_16x16x32_bf16 v[14:17], v[110:113], v[228:231], v[14:17]
	v_mfma_f32_16x16x32_bf16 v[10:13], v[134:137], v[228:231], v[10:13]
	v_mfma_f32_16x16x32_bf16 v[54:57], v[146:149], v[162:165], 0
	v_mfma_f32_16x16x32_bf16 v[50:53], v[154:157], v[162:165], 0
	v_mfma_f32_16x16x32_bf16 v[38:41], v[146:149], v[170:173], 0
	v_mfma_f32_16x16x32_bf16 v[34:37], v[154:157], v[170:173], 0
	v_mfma_f32_16x16x32_bf16 v[22:25], v[146:149], v[178:181], 0
	v_mfma_f32_16x16x32_bf16 v[18:21], v[154:157], v[178:181], 0
	v_mfma_f32_16x16x32_bf16 v[6:9], v[146:149], v[224:227], 0
	v_mfma_f32_16x16x32_bf16 v[2:5], v[154:157], v[224:227], 0
	v_mfma_f32_16x16x32_bf16 v[54:57], v[150:153], v[166:169], v[54:57]
	v_mfma_f32_16x16x32_bf16 v[50:53], v[158:161], v[166:169], v[50:53]
	v_mfma_f32_16x16x32_bf16 v[38:41], v[150:153], v[174:177], v[38:41]
	v_mfma_f32_16x16x32_bf16 v[34:37], v[158:161], v[174:177], v[34:37]
	v_mfma_f32_16x16x32_bf16 v[22:25], v[150:153], v[182:185], v[22:25]
	v_mfma_f32_16x16x32_bf16 v[18:21], v[158:161], v[182:185], v[18:21]
	v_mfma_f32_16x16x32_bf16 v[6:9], v[150:153], v[228:231], v[6:9]
	v_mfma_f32_16x16x32_bf16 v[2:5], v[158:161], v[228:231], v[2:5]
	s_barrier
	s_setprio 0
	s_add_i32 s47, 0, 0x18000
	v_add_u32_e32 v0, s47, v221
	s_add_i32 s68, 0, 0x1c000
	ds_read_b128 v[106:109], v0
	ds_read_b128 v[110:113], v0 offset:1024
	ds_read_b128 v[126:129], v0 offset:2048
	ds_read_b128 v[134:137], v0 offset:3072
	v_add_u32_e32 v0, s68, v221
	ds_read_b128 v[146:149], v0
	ds_read_b128 v[150:153], v0 offset:1024
	ds_read_b128 v[154:157], v0 offset:2048
	ds_read_b128 v[158:161], v0 offset:3072
	s_add_u32 s56, s56, 0x40000
	s_addc_u32 s57, s57, 0
	s_mov_b32 m0, s61
	v_lshl_add_u64 v[246:247], s[56:57], 0, v[210:211]
	ds_read_b128 v[162:165], v222 offset:32768
	ds_read_b128 v[166:169], v222 offset:33792
	ds_read_b128 v[170:173], v222 offset:34816
	ds_read_b128 v[174:177], v222 offset:35840
	ds_read_b128 v[178:181], v222 offset:36864
	ds_read_b128 v[182:185], v222 offset:37888
	ds_read_b128 v[224:227], v222 offset:38912
	ds_read_b128 v[228:231], v222 offset:39936
	global_load_lds_dwordx4 v[246:247], off
	v_lshl_add_u64 v[246:247], s[56:57], 0, v[206:207]
	s_mov_b32 m0, s62
	s_nop 0
	global_load_lds_dwordx4 v[246:247], off
	s_waitcnt vmcnt(8)
	s_waitcnt lgkmcnt(0)
	s_setprio 1
	s_barrier
	v_mfma_f32_16x16x32_bf16 v[142:145], v[106:109], v[162:165], v[142:145]
	v_mfma_f32_16x16x32_bf16 v[138:141], v[126:129], v[162:165], v[138:141]
	v_mfma_f32_16x16x32_bf16 v[118:121], v[106:109], v[170:173], v[118:121]
	v_mfma_f32_16x16x32_bf16 v[114:117], v[126:129], v[170:173], v[114:117]
	v_mfma_f32_16x16x32_bf16 v[94:97], v[106:109], v[178:181], v[94:97]
	v_mfma_f32_16x16x32_bf16 v[90:93], v[126:129], v[178:181], v[90:93]
	v_mfma_f32_16x16x32_bf16 v[78:81], v[106:109], v[224:227], v[78:81]
	v_mfma_f32_16x16x32_bf16 v[74:77], v[126:129], v[224:227], v[74:77]
	v_mfma_f32_16x16x32_bf16 v[142:145], v[110:113], v[166:169], v[142:145]
	v_mfma_f32_16x16x32_bf16 v[138:141], v[134:137], v[166:169], v[138:141]
	v_mfma_f32_16x16x32_bf16 v[118:121], v[110:113], v[174:177], v[118:121]
	v_mfma_f32_16x16x32_bf16 v[114:117], v[134:137], v[174:177], v[114:117]
	v_mfma_f32_16x16x32_bf16 v[94:97], v[110:113], v[182:185], v[94:97]
	v_mfma_f32_16x16x32_bf16 v[90:93], v[134:137], v[182:185], v[90:93]
	v_mfma_f32_16x16x32_bf16 v[78:81], v[110:113], v[228:231], v[78:81]
	v_mfma_f32_16x16x32_bf16 v[74:77], v[134:137], v[228:231], v[74:77]
	v_mfma_f32_16x16x32_bf16 v[130:133], v[146:149], v[162:165], v[130:133]
	v_mfma_f32_16x16x32_bf16 v[122:125], v[154:157], v[162:165], v[122:125]
	v_mfma_f32_16x16x32_bf16 v[102:105], v[146:149], v[170:173], v[102:105]
	v_mfma_f32_16x16x32_bf16 v[98:101], v[154:157], v[170:173], v[98:101]
	v_mfma_f32_16x16x32_bf16 v[86:89], v[146:149], v[178:181], v[86:89]
	v_mfma_f32_16x16x32_bf16 v[82:85], v[154:157], v[178:181], v[82:85]
	v_mfma_f32_16x16x32_bf16 v[70:73], v[146:149], v[224:227], v[70:73]
	v_mfma_f32_16x16x32_bf16 v[66:69], v[154:157], v[224:227], v[66:69]
	v_mfma_f32_16x16x32_bf16 v[130:133], v[150:153], v[166:169], v[130:133]
	v_mfma_f32_16x16x32_bf16 v[122:125], v[158:161], v[166:169], v[122:125]
	v_mfma_f32_16x16x32_bf16 v[102:105], v[150:153], v[174:177], v[102:105]
	v_mfma_f32_16x16x32_bf16 v[98:101], v[158:161], v[174:177], v[98:101]
	v_mfma_f32_16x16x32_bf16 v[86:89], v[150:153], v[182:185], v[86:89]
	v_mfma_f32_16x16x32_bf16 v[82:85], v[158:161], v[182:185], v[82:85]
	v_mfma_f32_16x16x32_bf16 v[70:73], v[150:153], v[228:231], v[70:73]
	v_mfma_f32_16x16x32_bf16 v[66:69], v[158:161], v[228:231], v[66:69]
	s_barrier
	s_setprio 0
	s_add_i32 s47, s47, s58
	v_lshl_add_u64 v[216:217], v[216:217], 0, s[16:17]
	s_mov_b32 m0, s47
	ds_read_b128 v[162:165], v222 offset:49152
	ds_read_b128 v[166:169], v222 offset:50176
	ds_read_b128 v[170:173], v222 offset:51200
	ds_read_b128 v[174:177], v222 offset:52224
	ds_read_b128 v[178:181], v222 offset:53248
	ds_read_b128 v[182:185], v222 offset:54272
	ds_read_b128 v[224:227], v222 offset:55296
	ds_read_b128 v[228:231], v222 offset:56320
	global_load_lds_dwordx4 v[216:217], off
	s_add_i32 m0, s47, 0x2000
	s_add_u32 s54, s54, 0x40080
	v_lshl_add_u64 v[216:217], v[240:241], 0, s[16:17]
	s_addc_u32 s55, s55, 0
	s_add_i32 s47, s68, s58
	global_load_lds_dwordx4 v[216:217], off
	v_lshl_add_u64 v[216:217], s[54:55], 0, v[208:209]
	s_mov_b32 m0, s47
	s_nop 0
	global_load_lds_dwordx4 v[216:217], off
	v_lshl_add_u64 v[216:217], s[54:55], 0, v[204:205]
	s_add_i32 m0, s47, 0x2000
	s_nop 0
	global_load_lds_dwordx4 v[216:217], off
	v_lshl_add_u64 v[216:217], v[242:243], 0, s[16:17]
	s_mov_b32 m0, s65
	s_nop 0
	global_load_lds_dwordx4 v[216:217], off
	v_lshl_add_u64 v[216:217], v[244:245], 0, s[16:17]
	s_mov_b32 m0, s66
	s_nop 0
	global_load_lds_dwordx4 v[216:217], off
	s_waitcnt vmcnt(8)
	s_waitcnt lgkmcnt(0)
	s_setprio 1
	s_barrier
	v_mfma_f32_16x16x32_bf16 v[62:65], v[106:109], v[162:165], v[62:65]
	v_mfma_f32_16x16x32_bf16 v[58:61], v[126:129], v[162:165], v[58:61]
	v_mfma_f32_16x16x32_bf16 v[46:49], v[106:109], v[170:173], v[46:49]
	v_mfma_f32_16x16x32_bf16 v[42:45], v[126:129], v[170:173], v[42:45]
	v_mfma_f32_16x16x32_bf16 v[30:33], v[106:109], v[178:181], v[30:33]
	v_mfma_f32_16x16x32_bf16 v[26:29], v[126:129], v[178:181], v[26:29]
	v_mfma_f32_16x16x32_bf16 v[14:17], v[106:109], v[224:227], v[14:17]
	v_mfma_f32_16x16x32_bf16 v[10:13], v[126:129], v[224:227], v[10:13]
	v_mfma_f32_16x16x32_bf16 v[62:65], v[110:113], v[166:169], v[62:65]
	v_mfma_f32_16x16x32_bf16 v[58:61], v[134:137], v[166:169], v[58:61]
	v_mfma_f32_16x16x32_bf16 v[46:49], v[110:113], v[174:177], v[46:49]
	v_mfma_f32_16x16x32_bf16 v[42:45], v[134:137], v[174:177], v[42:45]
	v_mfma_f32_16x16x32_bf16 v[30:33], v[110:113], v[182:185], v[30:33]
	v_mfma_f32_16x16x32_bf16 v[26:29], v[134:137], v[182:185], v[26:29]
	v_mfma_f32_16x16x32_bf16 v[14:17], v[110:113], v[228:231], v[14:17]
	v_mfma_f32_16x16x32_bf16 v[10:13], v[134:137], v[228:231], v[10:13]
	v_mfma_f32_16x16x32_bf16 v[54:57], v[146:149], v[162:165], v[54:57]
	v_mfma_f32_16x16x32_bf16 v[50:53], v[154:157], v[162:165], v[50:53]
	v_mfma_f32_16x16x32_bf16 v[38:41], v[146:149], v[170:173], v[38:41]
	v_mfma_f32_16x16x32_bf16 v[34:37], v[154:157], v[170:173], v[34:37]
	v_mfma_f32_16x16x32_bf16 v[22:25], v[146:149], v[178:181], v[22:25]
	v_mfma_f32_16x16x32_bf16 v[18:21], v[154:157], v[178:181], v[18:21]
	v_mfma_f32_16x16x32_bf16 v[6:9], v[146:149], v[224:227], v[6:9]
	v_mfma_f32_16x16x32_bf16 v[2:5], v[154:157], v[224:227], v[2:5]
	v_mfma_f32_16x16x32_bf16 v[54:57], v[150:153], v[166:169], v[54:57]
	v_mfma_f32_16x16x32_bf16 v[50:53], v[158:161], v[166:169], v[50:53]
	v_mfma_f32_16x16x32_bf16 v[38:41], v[150:153], v[174:177], v[38:41]
	v_mfma_f32_16x16x32_bf16 v[34:37], v[158:161], v[174:177], v[34:37]
	v_mfma_f32_16x16x32_bf16 v[22:25], v[150:153], v[182:185], v[22:25]
	v_mfma_f32_16x16x32_bf16 v[18:21], v[158:161], v[182:185], v[18:21]
	v_mfma_f32_16x16x32_bf16 v[6:9], v[150:153], v[228:231], v[6:9]
	v_mfma_f32_16x16x32_bf16 v[2:5], v[158:161], v[228:231], v[2:5]
	s_barrier
	s_setprio 0
	s_add_i32 s45, s45, 2
	s_add_u32 s52, s52, 0x100
	s_addc_u32 s53, s53, 0
	s_add_u32 s18, s18, 0x100
	s_addc_u32 s19, s19, 0
	s_cmp_gt_u32 s45, 13
	.p2align 6

.Lrb5_skip:
	s_add_u32 s52, s50, 0xfffc0080
	s_addc_u32 s53, s51, -1
	s_add_i32 s67, 0, 0x10000
	s_cmp_eq_u32 s66, 12
	s_cselect_b32 s55, s45, s53
	s_cselect_b32 s54, s62, s52
	v_add_u32_e32 v0, s67, v144
	s_cselect_b32 s53, s43, s65
	s_cselect_b32 s52, s63, s64
	s_add_i32 s70, 0, 0x14000
	ds_read_b128 v[146:149], v0
	ds_read_b128 v[150:153], v0 offset:1024
	ds_read_b128 v[154:157], v0 offset:2048
	ds_read_b128 v[158:161], v0 offset:3072
	v_add_u32_e32 v0, s70, v144
	ds_read_b128 v[162:165], v0
	ds_read_b128 v[166:169], v0 offset:1024
	ds_read_b128 v[170:173], v0 offset:2048
	ds_read_b128 v[174:177], v0 offset:3072
	s_add_i32 m0, s5, 0xc000
	ds_read_b128 v[178:181], v145
	ds_read_b128 v[182:185], v145 offset:1024
	ds_read_b128 v[204:207], v145 offset:2048
	ds_read_b128 v[208:211], v145 offset:3072
	ds_read_b128 v[212:215], v145 offset:4096
	ds_read_b128 v[220:223], v145 offset:5120
	ds_read_b128 v[224:227], v145 offset:6144
	ds_read_b128 v[228:231], v145 offset:7168
	global_load_lds_dwordx4 v138, s[50:51]
	s_add_i32 m0, s5, 0xe000
	s_nop 0
	global_load_lds_dwordx4 v140, s[50:51]
	s_waitcnt vmcnt(8)
	s_waitcnt lgkmcnt(0)
	s_setprio 1
	s_barrier
	v_mfma_f32_16x16x32_bf16 v[118:121], v[146:149], v[178:181], 0
	v_mfma_f32_16x16x32_bf16 v[114:117], v[154:157], v[178:181], 0
	v_mfma_f32_16x16x32_bf16 v[110:113], v[146:149], v[204:207], 0
	v_mfma_f32_16x16x32_bf16 v[102:105], v[154:157], v[204:207], 0
	v_mfma_f32_16x16x32_bf16 v[94:97], v[146:149], v[212:215], 0
	v_mfma_f32_16x16x32_bf16 v[86:89], v[154:157], v[212:215], 0
	v_mfma_f32_16x16x32_bf16 v[78:81], v[146:149], v[224:227], 0
	v_mfma_f32_16x16x32_bf16 v[70:73], v[154:157], v[224:227], 0
	v_mfma_f32_16x16x32_bf16 v[118:121], v[150:153], v[182:185], v[118:121]
	v_mfma_f32_16x16x32_bf16 v[114:117], v[158:161], v[182:185], v[114:117]
	v_mfma_f32_16x16x32_bf16 v[110:113], v[150:153], v[208:211], v[110:113]
	v_mfma_f32_16x16x32_bf16 v[102:105], v[158:161], v[208:211], v[102:105]
	v_mfma_f32_16x16x32_bf16 v[94:97], v[150:153], v[220:223], v[94:97]
	v_mfma_f32_16x16x32_bf16 v[86:89], v[158:161], v[220:223], v[86:89]
	v_mfma_f32_16x16x32_bf16 v[78:81], v[150:153], v[228:231], v[78:81]
	v_mfma_f32_16x16x32_bf16 v[70:73], v[158:161], v[228:231], v[70:73]
	v_mfma_f32_16x16x32_bf16 v[126:129], v[162:165], v[178:181], 0
	v_mfma_f32_16x16x32_bf16 v[122:125], v[170:173], v[178:181], 0
	v_mfma_f32_16x16x32_bf16 v[106:109], v[162:165], v[204:207], 0
	v_mfma_f32_16x16x32_bf16 v[98:101], v[170:173], v[204:207], 0
	v_mfma_f32_16x16x32_bf16 v[90:93], v[162:165], v[212:215], 0
	v_mfma_f32_16x16x32_bf16 v[82:85], v[170:173], v[212:215], 0
	v_mfma_f32_16x16x32_bf16 v[74:77], v[162:165], v[224:227], 0
	v_mfma_f32_16x16x32_bf16 v[66:69], v[170:173], v[224:227], 0
	v_mfma_f32_16x16x32_bf16 v[126:129], v[166:169], v[182:185], v[126:129]
	v_mfma_f32_16x16x32_bf16 v[122:125], v[174:177], v[182:185], v[122:125]
	v_mfma_f32_16x16x32_bf16 v[106:109], v[166:169], v[208:211], v[106:109]
	v_mfma_f32_16x16x32_bf16 v[98:101], v[174:177], v[208:211], v[98:101]
	v_mfma_f32_16x16x32_bf16 v[90:93], v[166:169], v[220:223], v[90:93]
	v_mfma_f32_16x16x32_bf16 v[82:85], v[174:177], v[220:223], v[82:85]
	v_mfma_f32_16x16x32_bf16 v[74:77], v[166:169], v[228:231], v[74:77]
	v_mfma_f32_16x16x32_bf16 v[66:69], v[174:177], v[228:231], v[66:69]
	s_barrier
	s_setprio 0
	s_add_i32 s67, s67, s4
	s_mov_b32 m0, s67
	ds_read_b128 v[178:181], v145 offset:16384
	ds_read_b128 v[182:185], v145 offset:17408
	ds_read_b128 v[204:207], v145 offset:18432
	ds_read_b128 v[208:211], v145 offset:19456
	ds_read_b128 v[212:215], v145 offset:20480
	ds_read_b128 v[220:223], v145 offset:21504
	ds_read_b128 v[224:227], v145 offset:22528
	ds_read_b128 v[228:231], v145 offset:23552
	global_load_lds_dwordx4 v134, s[52:53]
	s_add_i32 m0, s67, 0x2000
	s_add_u32 s68, s52, 0x40000
	s_addc_u32 s69, s53, 0
	s_add_i32 s67, s70, s4
	global_load_lds_dwordx4 v130, s[52:53]
	s_mov_b32 m0, s67
	s_nop 0
	global_load_lds_dwordx4 v134, s[68:69]
	s_add_i32 m0, s67, 0x2000
	s_nop 0
	global_load_lds_dwordx4 v130, s[68:69]
	s_mov_b32 m0, s5
	s_nop 0
	global_load_lds_dwordx4 v136, s[54:55]
	s_mov_b32 m0, s6
	s_nop 0
	global_load_lds_dwordx4 v132, s[54:55]
	s_waitcnt vmcnt(8)
	s_waitcnt lgkmcnt(0)
	s_setprio 1
	s_barrier
	v_mfma_f32_16x16x32_bf16 v[62:65], v[146:149], v[178:181], 0
	v_mfma_f32_16x16x32_bf16 v[54:57], v[154:157], v[178:181], 0
	v_mfma_f32_16x16x32_bf16 v[46:49], v[146:149], v[204:207], 0
	v_mfma_f32_16x16x32_bf16 v[38:41], v[154:157], v[204:207], 0
	v_mfma_f32_16x16x32_bf16 v[30:33], v[146:149], v[212:215], 0
	v_mfma_f32_16x16x32_bf16 v[22:25], v[154:157], v[212:215], 0
	v_mfma_f32_16x16x32_bf16 v[14:17], v[146:149], v[224:227], 0
	v_mfma_f32_16x16x32_bf16 v[6:9], v[154:157], v[224:227], 0
	v_mfma_f32_16x16x32_bf16 v[62:65], v[150:153], v[182:185], v[62:65]
	v_mfma_f32_16x16x32_bf16 v[54:57], v[158:161], v[182:185], v[54:57]
	v_mfma_f32_16x16x32_bf16 v[46:49], v[150:153], v[208:211], v[46:49]
	v_mfma_f32_16x16x32_bf16 v[38:41], v[158:161], v[208:211], v[38:41]
	v_mfma_f32_16x16x32_bf16 v[30:33], v[150:153], v[220:223], v[30:33]
	v_mfma_f32_16x16x32_bf16 v[22:25], v[158:161], v[220:223], v[22:25]
	v_mfma_f32_16x16x32_bf16 v[14:17], v[150:153], v[228:231], v[14:17]
	v_mfma_f32_16x16x32_bf16 v[6:9], v[158:161], v[228:231], v[6:9]
	v_mfma_f32_16x16x32_bf16 v[58:61], v[162:165], v[178:181], 0
	v_mfma_f32_16x16x32_bf16 v[50:53], v[170:173], v[178:181], 0
	v_mfma_f32_16x16x32_bf16 v[42:45], v[162:165], v[204:207], 0
	v_mfma_f32_16x16x32_bf16 v[34:37], v[170:173], v[204:207], 0
	v_mfma_f32_16x16x32_bf16 v[26:29], v[162:165], v[212:215], 0
	v_mfma_f32_16x16x32_bf16 v[18:21], v[170:173], v[212:215], 0
	v_mfma_f32_16x16x32_bf16 v[10:13], v[162:165], v[224:227], 0
	v_mfma_f32_16x16x32_bf16 v[2:5], v[170:173], v[224:227], 0
	v_mfma_f32_16x16x32_bf16 v[58:61], v[166:169], v[182:185], v[58:61]
	v_mfma_f32_16x16x32_bf16 v[50:53], v[174:177], v[182:185], v[50:53]
	v_mfma_f32_16x16x32_bf16 v[42:45], v[166:169], v[208:211], v[42:45]
	v_mfma_f32_16x16x32_bf16 v[34:37], v[174:177], v[208:211], v[34:37]
	v_mfma_f32_16x16x32_bf16 v[26:29], v[166:169], v[220:223], v[26:29]
	v_mfma_f32_16x16x32_bf16 v[18:21], v[174:177], v[220:223], v[18:21]
	v_mfma_f32_16x16x32_bf16 v[10:13], v[166:169], v[228:231], v[10:13]
	v_mfma_f32_16x16x32_bf16 v[2:5], v[174:177], v[228:231], v[2:5]
	s_barrier
	s_setprio 0
	s_add_i32 s67, 0, 0x18000
	v_add_u32_e32 v0, s67, v144
	s_add_i32 s68, 0, 0x1c000
	ds_read_b128 v[146:149], v0
	ds_read_b128 v[150:153], v0 offset:1024
	ds_read_b128 v[154:157], v0 offset:2048
	ds_read_b128 v[158:161], v0 offset:3072
	v_add_u32_e32 v0, s68, v144
	ds_read_b128 v[162:165], v0
	ds_read_b128 v[166:169], v0 offset:1024
	ds_read_b128 v[170:173], v0 offset:2048
	ds_read_b128 v[174:177], v0 offset:3072
	s_add_u32 s54, s54, 0x40000
	s_addc_u32 s55, s55, 0
	s_mov_b32 m0, s7
	ds_read_b128 v[178:181], v145 offset:32768
	ds_read_b128 v[182:185], v145 offset:33792
	ds_read_b128 v[204:207], v145 offset:34816
	ds_read_b128 v[208:211], v145 offset:35840
	ds_read_b128 v[212:215], v145 offset:36864
	ds_read_b128 v[220:223], v145 offset:37888
	ds_read_b128 v[224:227], v145 offset:38912
	ds_read_b128 v[228:231], v145 offset:39936
	global_load_lds_dwordx4 v136, s[54:55]
	s_mov_b32 m0, s56
	s_nop 0
	global_load_lds_dwordx4 v132, s[54:55]
	s_waitcnt vmcnt(8)
	s_waitcnt lgkmcnt(0)
	s_setprio 1
	s_barrier
	v_mfma_f32_16x16x32_bf16 v[118:121], v[146:149], v[178:181], v[118:121]
	v_mfma_f32_16x16x32_bf16 v[114:117], v[154:157], v[178:181], v[114:117]
	v_mfma_f32_16x16x32_bf16 v[110:113], v[146:149], v[204:207], v[110:113]
	v_mfma_f32_16x16x32_bf16 v[102:105], v[154:157], v[204:207], v[102:105]
	v_mfma_f32_16x16x32_bf16 v[94:97], v[146:149], v[212:215], v[94:97]
	v_mfma_f32_16x16x32_bf16 v[86:89], v[154:157], v[212:215], v[86:89]
	v_mfma_f32_16x16x32_bf16 v[78:81], v[146:149], v[224:227], v[78:81]
	v_mfma_f32_16x16x32_bf16 v[70:73], v[154:157], v[224:227], v[70:73]
	v_mfma_f32_16x16x32_bf16 v[118:121], v[150:153], v[182:185], v[118:121]
	v_mfma_f32_16x16x32_bf16 v[114:117], v[158:161], v[182:185], v[114:117]
	v_mfma_f32_16x16x32_bf16 v[110:113], v[150:153], v[208:211], v[110:113]
	v_mfma_f32_16x16x32_bf16 v[102:105], v[158:161], v[208:211], v[102:105]
	v_mfma_f32_16x16x32_bf16 v[94:97], v[150:153], v[220:223], v[94:97]
	v_mfma_f32_16x16x32_bf16 v[86:89], v[158:161], v[220:223], v[86:89]
	v_mfma_f32_16x16x32_bf16 v[78:81], v[150:153], v[228:231], v[78:81]
	v_mfma_f32_16x16x32_bf16 v[70:73], v[158:161], v[228:231], v[70:73]
	v_mfma_f32_16x16x32_bf16 v[126:129], v[162:165], v[178:181], v[126:129]
	v_mfma_f32_16x16x32_bf16 v[122:125], v[170:173], v[178:181], v[122:125]
	v_mfma_f32_16x16x32_bf16 v[106:109], v[162:165], v[204:207], v[106:109]
	v_mfma_f32_16x16x32_bf16 v[98:101], v[170:173], v[204:207], v[98:101]
	v_mfma_f32_16x16x32_bf16 v[90:93], v[162:165], v[212:215], v[90:93]
	v_mfma_f32_16x16x32_bf16 v[82:85], v[170:173], v[212:215], v[82:85]
	v_mfma_f32_16x16x32_bf16 v[74:77], v[162:165], v[224:227], v[74:77]
	v_mfma_f32_16x16x32_bf16 v[66:69], v[170:173], v[224:227], v[66:69]
	v_mfma_f32_16x16x32_bf16 v[126:129], v[166:169], v[182:185], v[126:129]
	v_mfma_f32_16x16x32_bf16 v[122:125], v[174:177], v[182:185], v[122:125]
	v_mfma_f32_16x16x32_bf16 v[106:109], v[166:169], v[208:211], v[106:109]
	v_mfma_f32_16x16x32_bf16 v[98:101], v[174:177], v[208:211], v[98:101]
	v_mfma_f32_16x16x32_bf16 v[90:93], v[166:169], v[220:223], v[90:93]
	v_mfma_f32_16x16x32_bf16 v[82:85], v[174:177], v[220:223], v[82:85]
	v_mfma_f32_16x16x32_bf16 v[74:77], v[166:169], v[228:231], v[74:77]
	v_mfma_f32_16x16x32_bf16 v[66:69], v[174:177], v[228:231], v[66:69]
	s_barrier
	s_setprio 0
	s_add_i32 s69, s67, s4
	s_add_u32 s52, s52, 0x80
	s_addc_u32 s53, s53, 0
	s_mov_b32 m0, s69
	ds_read_b128 v[178:181], v145 offset:49152
	ds_read_b128 v[182:185], v145 offset:50176
	ds_read_b128 v[204:207], v145 offset:51200
	ds_read_b128 v[208:211], v145 offset:52224
	ds_read_b128 v[212:215], v145 offset:53248
	ds_read_b128 v[220:223], v145 offset:54272
	ds_read_b128 v[224:227], v145 offset:55296
	ds_read_b128 v[228:231], v145 offset:56320
	global_load_lds_dwordx4 v134, s[52:53]
	s_add_i32 m0, s69, 0x2000
	s_add_i32 s69, s68, s4
	global_load_lds_dwordx4 v130, s[52:53]
	s_add_u32 s52, s52, 0x40000
	s_addc_u32 s53, s53, 0
	s_mov_b32 m0, s69
	s_sub_u32 s54, s54, 0x3ff80
	global_load_lds_dwordx4 v134, s[52:53]
	s_subb_u32 s55, s55, 0
	s_add_i32 m0, s69, 0x2000
	s_nop 0
	global_load_lds_dwordx4 v130, s[52:53]
	s_mov_b32 m0, s59
	s_nop 0
	global_load_lds_dwordx4 v136, s[54:55]
	s_mov_b32 m0, s60
	s_nop 0
	global_load_lds_dwordx4 v132, s[54:55]
	s_waitcnt vmcnt(8)
	s_waitcnt lgkmcnt(0)
	s_setprio 1
	s_barrier
	v_mfma_f32_16x16x32_bf16 v[62:65], v[146:149], v[178:181], v[62:65]
	v_mfma_f32_16x16x32_bf16 v[54:57], v[154:157], v[178:181], v[54:57]
	v_mfma_f32_16x16x32_bf16 v[46:49], v[146:149], v[204:207], v[46:49]
	v_mfma_f32_16x16x32_bf16 v[38:41], v[154:157], v[204:207], v[38:41]
	v_mfma_f32_16x16x32_bf16 v[30:33], v[146:149], v[212:215], v[30:33]
	v_mfma_f32_16x16x32_bf16 v[22:25], v[154:157], v[212:215], v[22:25]
	v_mfma_f32_16x16x32_bf16 v[14:17], v[146:149], v[224:227], v[14:17]
	v_mfma_f32_16x16x32_bf16 v[6:9], v[154:157], v[224:227], v[6:9]
	v_mfma_f32_16x16x32_bf16 v[62:65], v[150:153], v[182:185], v[62:65]
	v_mfma_f32_16x16x32_bf16 v[54:57], v[158:161], v[182:185], v[54:57]
	v_mfma_f32_16x16x32_bf16 v[46:49], v[150:153], v[208:211], v[46:49]
	v_mfma_f32_16x16x32_bf16 v[38:41], v[158:161], v[208:211], v[38:41]
	v_mfma_f32_16x16x32_bf16 v[30:33], v[150:153], v[220:223], v[30:33]
	v_mfma_f32_16x16x32_bf16 v[22:25], v[158:161], v[220:223], v[22:25]
	v_mfma_f32_16x16x32_bf16 v[14:17], v[150:153], v[228:231], v[14:17]
	v_mfma_f32_16x16x32_bf16 v[6:9], v[158:161], v[228:231], v[6:9]
	v_mfma_f32_16x16x32_bf16 v[58:61], v[162:165], v[178:181], v[58:61]
	v_mfma_f32_16x16x32_bf16 v[50:53], v[170:173], v[178:181], v[50:53]
	v_mfma_f32_16x16x32_bf16 v[42:45], v[162:165], v[204:207], v[42:45]
	v_mfma_f32_16x16x32_bf16 v[34:37], v[170:173], v[204:207], v[34:37]
	v_mfma_f32_16x16x32_bf16 v[26:29], v[162:165], v[212:215], v[26:29]
	v_mfma_f32_16x16x32_bf16 v[18:21], v[170:173], v[212:215], v[18:21]
	v_mfma_f32_16x16x32_bf16 v[10:13], v[162:165], v[224:227], v[10:13]
	v_mfma_f32_16x16x32_bf16 v[2:5], v[170:173], v[224:227], v[2:5]
	v_mfma_f32_16x16x32_bf16 v[58:61], v[166:169], v[182:185], v[58:61]
	v_mfma_f32_16x16x32_bf16 v[50:53], v[174:177], v[182:185], v[50:53]
	v_mfma_f32_16x16x32_bf16 v[42:45], v[166:169], v[208:211], v[42:45]
	v_mfma_f32_16x16x32_bf16 v[34:37], v[174:177], v[208:211], v[34:37]
	v_mfma_f32_16x16x32_bf16 v[26:29], v[166:169], v[220:223], v[26:29]
	v_mfma_f32_16x16x32_bf16 v[18:21], v[174:177], v[220:223], v[18:21]
	v_mfma_f32_16x16x32_bf16 v[10:13], v[166:169], v[228:231], v[10:13]
	v_mfma_f32_16x16x32_bf16 v[2:5], v[174:177], v[228:231], v[2:5]
	s_barrier
	s_setprio 0
	s_add_i32 s66, s66, 2
	s_add_u32 s50, s50, 0x100
	s_addc_u32 s51, s51, 0
	s_add_u32 s64, s64, 0x100
	s_addc_u32 s65, s65, 0
	s_cmp_gt_u32 s66, 13
	.p2align 6

.Lrb6_skip:
	s_add_u32 s0, s44, 0x100
	s_addc_u32 s1, s45, 0
	s_add_i32 s63, 0, 0x10000
	s_cmp_eq_u32 s62, 40
	s_cselect_b32 s51, s41, s1
	s_cselect_b32 s50, s40, s0
	v_add_u32_e32 v0, s63, v221
	s_cselect_b32 s49, s43, s47
	s_cselect_b32 s48, s42, s7
	s_add_i32 s64, 0, 0x14000
	ds_read_b128 v[106:109], v0
	ds_read_b128 v[110:113], v0 offset:1024
	ds_read_b128 v[126:129], v0 offset:2048
	ds_read_b128 v[134:137], v0 offset:3072
	v_add_u32_e32 v0, s64, v221
	ds_read_b128 v[146:149], v0
	ds_read_b128 v[150:153], v0 offset:1024
	ds_read_b128 v[154:157], v0 offset:2048
	ds_read_b128 v[158:161], v0 offset:3072
	v_lshl_add_u64 v[216:217], s[44:45], 0, v[212:213]
	s_add_i32 m0, s53, 0xc000
	ds_read_b128 v[162:165], v222
	ds_read_b128 v[166:169], v222 offset:1024
	ds_read_b128 v[170:173], v222 offset:2048
	ds_read_b128 v[174:177], v222 offset:3072
	ds_read_b128 v[178:181], v222 offset:4096
	ds_read_b128 v[182:185], v222 offset:5120
	ds_read_b128 v[224:227], v222 offset:6144
	ds_read_b128 v[228:231], v222 offset:7168
	global_load_lds_dwordx4 v[216:217], off
	v_lshl_add_u64 v[216:217], s[44:45], 0, v[214:215]
	s_add_i32 m0, s53, 0xe000
	s_nop 0
	global_load_lds_dwordx4 v[216:217], off
	s_waitcnt vmcnt(8)
	s_waitcnt lgkmcnt(0)
	s_setprio 1
	s_barrier
	v_mfma_f32_16x16x32_bf16 v[142:145], v[106:109], v[162:165], 0
	v_mfma_f32_16x16x32_bf16 v[138:141], v[126:129], v[162:165], 0
	v_mfma_f32_16x16x32_bf16 v[118:121], v[106:109], v[170:173], 0
	v_mfma_f32_16x16x32_bf16 v[114:117], v[126:129], v[170:173], 0
	v_mfma_f32_16x16x32_bf16 v[94:97], v[106:109], v[178:181], 0
	v_mfma_f32_16x16x32_bf16 v[90:93], v[126:129], v[178:181], 0
	v_mfma_f32_16x16x32_bf16 v[78:81], v[106:109], v[224:227], 0
	v_mfma_f32_16x16x32_bf16 v[74:77], v[126:129], v[224:227], 0
	v_mfma_f32_16x16x32_bf16 v[142:145], v[110:113], v[166:169], v[142:145]
	v_mfma_f32_16x16x32_bf16 v[138:141], v[134:137], v[166:169], v[138:141]
	v_mfma_f32_16x16x32_bf16 v[118:121], v[110:113], v[174:177], v[118:121]
	v_mfma_f32_16x16x32_bf16 v[114:117], v[134:137], v[174:177], v[114:117]
	v_mfma_f32_16x16x32_bf16 v[94:97], v[110:113], v[182:185], v[94:97]
	v_mfma_f32_16x16x32_bf16 v[90:93], v[134:137], v[182:185], v[90:93]
	v_mfma_f32_16x16x32_bf16 v[78:81], v[110:113], v[228:231], v[78:81]
	v_mfma_f32_16x16x32_bf16 v[74:77], v[134:137], v[228:231], v[74:77]
	v_mfma_f32_16x16x32_bf16 v[130:133], v[146:149], v[162:165], 0
	v_mfma_f32_16x16x32_bf16 v[122:125], v[154:157], v[162:165], 0
	v_mfma_f32_16x16x32_bf16 v[102:105], v[146:149], v[170:173], 0
	v_mfma_f32_16x16x32_bf16 v[98:101], v[154:157], v[170:173], 0
	v_mfma_f32_16x16x32_bf16 v[86:89], v[146:149], v[178:181], 0
	v_mfma_f32_16x16x32_bf16 v[82:85], v[154:157], v[178:181], 0
	v_mfma_f32_16x16x32_bf16 v[70:73], v[146:149], v[224:227], 0
	v_mfma_f32_16x16x32_bf16 v[66:69], v[154:157], v[224:227], 0
	v_mfma_f32_16x16x32_bf16 v[130:133], v[150:153], v[166:169], v[130:133]
	v_mfma_f32_16x16x32_bf16 v[122:125], v[158:161], v[166:169], v[122:125]
	v_mfma_f32_16x16x32_bf16 v[102:105], v[150:153], v[174:177], v[102:105]
	v_mfma_f32_16x16x32_bf16 v[98:101], v[158:161], v[174:177], v[98:101]
	v_mfma_f32_16x16x32_bf16 v[86:89], v[150:153], v[182:185], v[86:89]
	v_mfma_f32_16x16x32_bf16 v[82:85], v[158:161], v[182:185], v[82:85]
	v_mfma_f32_16x16x32_bf16 v[70:73], v[150:153], v[228:231], v[70:73]
	v_mfma_f32_16x16x32_bf16 v[66:69], v[158:161], v[228:231], v[66:69]
	s_barrier
	s_setprio 0
	s_add_i32 s44, s63, s52
	v_lshl_add_u64 v[216:217], s[48:49], 0, v[208:209]
	s_mov_b32 m0, s44
	ds_read_b128 v[162:165], v222 offset:16384
	ds_read_b128 v[166:169], v222 offset:17408
	ds_read_b128 v[170:173], v222 offset:18432
	ds_read_b128 v[174:177], v222 offset:19456
	ds_read_b128 v[178:181], v222 offset:20480
	ds_read_b128 v[182:185], v222 offset:21504
	ds_read_b128 v[224:227], v222 offset:22528
	ds_read_b128 v[228:231], v222 offset:23552
	global_load_lds_dwordx4 v[216:217], off
	s_add_i32 m0, s44, 0x2000
	s_add_u32 s44, s48, 0xb0000
	v_lshl_add_u64 v[240:241], s[48:49], 0, v[204:205]
	s_addc_u32 s45, s49, 0
	s_add_i32 s63, s64, s52
	global_load_lds_dwordx4 v[240:241], off
	v_lshl_add_u64 v[242:243], s[44:45], 0, v[208:209]
	s_mov_b32 m0, s63
	v_lshl_add_u64 v[244:245], s[50:51], 0, v[206:207]
	global_load_lds_dwordx4 v[242:243], off
	v_lshl_add_u64 v[242:243], s[44:45], 0, v[204:205]
	s_add_i32 m0, s63, 0x2000
	s_nop 0
	global_load_lds_dwordx4 v[242:243], off
	v_lshl_add_u64 v[242:243], s[50:51], 0, v[210:211]
	s_mov_b32 m0, s53
	s_nop 0
	global_load_lds_dwordx4 v[242:243], off
	s_mov_b32 m0, s54
	s_nop 0
	global_load_lds_dwordx4 v[244:245], off
	s_waitcnt vmcnt(8)
	s_waitcnt lgkmcnt(0)
	s_setprio 1
	s_barrier
	v_mfma_f32_16x16x32_bf16 v[62:65], v[106:109], v[162:165], 0
	v_mfma_f32_16x16x32_bf16 v[58:61], v[126:129], v[162:165], 0
	v_mfma_f32_16x16x32_bf16 v[46:49], v[106:109], v[170:173], 0
	v_mfma_f32_16x16x32_bf16 v[42:45], v[126:129], v[170:173], 0
	v_mfma_f32_16x16x32_bf16 v[30:33], v[106:109], v[178:181], 0
	v_mfma_f32_16x16x32_bf16 v[26:29], v[126:129], v[178:181], 0
	v_mfma_f32_16x16x32_bf16 v[14:17], v[106:109], v[224:227], 0
	v_mfma_f32_16x16x32_bf16 v[10:13], v[126:129], v[224:227], 0
	v_mfma_f32_16x16x32_bf16 v[62:65], v[110:113], v[166:169], v[62:65]
	v_mfma_f32_16x16x32_bf16 v[58:61], v[134:137], v[166:169], v[58:61]
	v_mfma_f32_16x16x32_bf16 v[46:49], v[110:113], v[174:177], v[46:49]
	v_mfma_f32_16x16x32_bf16 v[42:45], v[134:137], v[174:177], v[42:45]
	v_mfma_f32_16x16x32_bf16 v[30:33], v[110:113], v[182:185], v[30:33]
	v_mfma_f32_16x16x32_bf16 v[26:29], v[134:137], v[182:185], v[26:29]
	v_mfma_f32_16x16x32_bf16 v[14:17], v[110:113], v[228:231], v[14:17]
	v_mfma_f32_16x16x32_bf16 v[10:13], v[134:137], v[228:231], v[10:13]
	v_mfma_f32_16x16x32_bf16 v[54:57], v[146:149], v[162:165], 0
	v_mfma_f32_16x16x32_bf16 v[50:53], v[154:157], v[162:165], 0
	v_mfma_f32_16x16x32_bf16 v[38:41], v[146:149], v[170:173], 0
	v_mfma_f32_16x16x32_bf16 v[34:37], v[154:157], v[170:173], 0
	v_mfma_f32_16x16x32_bf16 v[22:25], v[146:149], v[178:181], 0
	v_mfma_f32_16x16x32_bf16 v[18:21], v[154:157], v[178:181], 0
	v_mfma_f32_16x16x32_bf16 v[6:9], v[146:149], v[224:227], 0
	v_mfma_f32_16x16x32_bf16 v[2:5], v[154:157], v[224:227], 0
	v_mfma_f32_16x16x32_bf16 v[54:57], v[150:153], v[166:169], v[54:57]
	v_mfma_f32_16x16x32_bf16 v[50:53], v[158:161], v[166:169], v[50:53]
	v_mfma_f32_16x16x32_bf16 v[38:41], v[150:153], v[174:177], v[38:41]
	v_mfma_f32_16x16x32_bf16 v[34:37], v[158:161], v[174:177], v[34:37]
	v_mfma_f32_16x16x32_bf16 v[22:25], v[150:153], v[182:185], v[22:25]
	v_mfma_f32_16x16x32_bf16 v[18:21], v[158:161], v[182:185], v[18:21]
	v_mfma_f32_16x16x32_bf16 v[6:9], v[150:153], v[228:231], v[6:9]
	v_mfma_f32_16x16x32_bf16 v[2:5], v[158:161], v[228:231], v[2:5]
	s_barrier
	s_setprio 0
	s_add_i32 s63, 0, 0x18000
	v_add_u32_e32 v0, s63, v221
	s_add_i32 s64, 0, 0x1c000
	ds_read_b128 v[106:109], v0
	ds_read_b128 v[110:113], v0 offset:1024
	ds_read_b128 v[126:129], v0 offset:2048
	ds_read_b128 v[134:137], v0 offset:3072
	v_add_u32_e32 v0, s64, v221
	ds_read_b128 v[146:149], v0
	ds_read_b128 v[150:153], v0 offset:1024
	ds_read_b128 v[154:157], v0 offset:2048
	ds_read_b128 v[158:161], v0 offset:3072
	s_add_u32 s44, s50, 0xb0000
	s_addc_u32 s45, s51, 0
	s_mov_b32 m0, s55
	v_lshl_add_u64 v[246:247], s[44:45], 0, v[210:211]
	ds_read_b128 v[162:165], v222 offset:32768
	ds_read_b128 v[166:169], v222 offset:33792
	ds_read_b128 v[170:173], v222 offset:34816
	ds_read_b128 v[174:177], v222 offset:35840
	ds_read_b128 v[178:181], v222 offset:36864
	ds_read_b128 v[182:185], v222 offset:37888
	ds_read_b128 v[224:227], v222 offset:38912
	ds_read_b128 v[228:231], v222 offset:39936
	global_load_lds_dwordx4 v[246:247], off
	v_lshl_add_u64 v[246:247], s[44:45], 0, v[206:207]
	s_mov_b32 m0, s56
	s_nop 0
	global_load_lds_dwordx4 v[246:247], off
	s_waitcnt vmcnt(8)
	s_waitcnt lgkmcnt(0)
	s_setprio 1
	s_barrier
	v_mfma_f32_16x16x32_bf16 v[142:145], v[106:109], v[162:165], v[142:145]
	v_mfma_f32_16x16x32_bf16 v[138:141], v[126:129], v[162:165], v[138:141]
	v_mfma_f32_16x16x32_bf16 v[118:121], v[106:109], v[170:173], v[118:121]
	v_mfma_f32_16x16x32_bf16 v[114:117], v[126:129], v[170:173], v[114:117]
	v_mfma_f32_16x16x32_bf16 v[94:97], v[106:109], v[178:181], v[94:97]
	v_mfma_f32_16x16x32_bf16 v[90:93], v[126:129], v[178:181], v[90:93]
	v_mfma_f32_16x16x32_bf16 v[78:81], v[106:109], v[224:227], v[78:81]
	v_mfma_f32_16x16x32_bf16 v[74:77], v[126:129], v[224:227], v[74:77]
	v_mfma_f32_16x16x32_bf16 v[142:145], v[110:113], v[166:169], v[142:145]
	v_mfma_f32_16x16x32_bf16 v[138:141], v[134:137], v[166:169], v[138:141]
	v_mfma_f32_16x16x32_bf16 v[118:121], v[110:113], v[174:177], v[118:121]
	v_mfma_f32_16x16x32_bf16 v[114:117], v[134:137], v[174:177], v[114:117]
	v_mfma_f32_16x16x32_bf16 v[94:97], v[110:113], v[182:185], v[94:97]
	v_mfma_f32_16x16x32_bf16 v[90:93], v[134:137], v[182:185], v[90:93]
	v_mfma_f32_16x16x32_bf16 v[78:81], v[110:113], v[228:231], v[78:81]
	v_mfma_f32_16x16x32_bf16 v[74:77], v[134:137], v[228:231], v[74:77]
	v_mfma_f32_16x16x32_bf16 v[130:133], v[146:149], v[162:165], v[130:133]
	v_mfma_f32_16x16x32_bf16 v[122:125], v[154:157], v[162:165], v[122:125]
	v_mfma_f32_16x16x32_bf16 v[102:105], v[146:149], v[170:173], v[102:105]
	v_mfma_f32_16x16x32_bf16 v[98:101], v[154:157], v[170:173], v[98:101]
	v_mfma_f32_16x16x32_bf16 v[86:89], v[146:149], v[178:181], v[86:89]
	v_mfma_f32_16x16x32_bf16 v[82:85], v[154:157], v[178:181], v[82:85]
	v_mfma_f32_16x16x32_bf16 v[70:73], v[146:149], v[224:227], v[70:73]
	v_mfma_f32_16x16x32_bf16 v[66:69], v[154:157], v[224:227], v[66:69]
	v_mfma_f32_16x16x32_bf16 v[130:133], v[150:153], v[166:169], v[130:133]
	v_mfma_f32_16x16x32_bf16 v[122:125], v[158:161], v[166:169], v[122:125]
	v_mfma_f32_16x16x32_bf16 v[102:105], v[150:153], v[174:177], v[102:105]
	v_mfma_f32_16x16x32_bf16 v[98:101], v[158:161], v[174:177], v[98:101]
	v_mfma_f32_16x16x32_bf16 v[86:89], v[150:153], v[182:185], v[86:89]
	v_mfma_f32_16x16x32_bf16 v[82:85], v[158:161], v[182:185], v[82:85]
	v_mfma_f32_16x16x32_bf16 v[70:73], v[150:153], v[228:231], v[70:73]
	v_mfma_f32_16x16x32_bf16 v[66:69], v[158:161], v[228:231], v[66:69]
	s_barrier
	s_setprio 0
	s_add_i32 s44, s63, s52
	v_lshl_add_u64 v[216:217], v[216:217], 0, s[16:17]
	s_mov_b32 m0, s44
	ds_read_b128 v[162:165], v222 offset:49152
	ds_read_b128 v[166:169], v222 offset:50176
	ds_read_b128 v[170:173], v222 offset:51200
	ds_read_b128 v[174:177], v222 offset:52224
	ds_read_b128 v[178:181], v222 offset:53248
	ds_read_b128 v[182:185], v222 offset:54272
	ds_read_b128 v[224:227], v222 offset:55296
	ds_read_b128 v[228:231], v222 offset:56320
	global_load_lds_dwordx4 v[216:217], off
	s_add_i32 m0, s44, 0x2000
	s_add_u32 s44, s48, 0xb0080
	v_lshl_add_u64 v[216:217], v[240:241], 0, s[16:17]
	s_addc_u32 s45, s49, 0
	s_add_i32 s48, s64, s52
	global_load_lds_dwordx4 v[216:217], off
	v_lshl_add_u64 v[216:217], s[44:45], 0, v[208:209]
	s_mov_b32 m0, s48
	s_nop 0
	global_load_lds_dwordx4 v[216:217], off
	v_lshl_add_u64 v[216:217], s[44:45], 0, v[204:205]
	s_add_i32 m0, s48, 0x2000
	s_nop 0
	global_load_lds_dwordx4 v[216:217], off
	v_lshl_add_u64 v[216:217], v[242:243], 0, s[16:17]
	s_mov_b32 m0, s59
	s_nop 0
	global_load_lds_dwordx4 v[216:217], off
	v_lshl_add_u64 v[216:217], v[244:245], 0, s[16:17]
	s_mov_b32 m0, s60
	s_nop 0
	global_load_lds_dwordx4 v[216:217], off
	s_waitcnt vmcnt(8)
	s_waitcnt lgkmcnt(0)
	s_setprio 1
	s_barrier
	v_mfma_f32_16x16x32_bf16 v[62:65], v[106:109], v[162:165], v[62:65]
	v_mfma_f32_16x16x32_bf16 v[58:61], v[126:129], v[162:165], v[58:61]
	v_mfma_f32_16x16x32_bf16 v[46:49], v[106:109], v[170:173], v[46:49]
	v_mfma_f32_16x16x32_bf16 v[42:45], v[126:129], v[170:173], v[42:45]
	v_mfma_f32_16x16x32_bf16 v[30:33], v[106:109], v[178:181], v[30:33]
	v_mfma_f32_16x16x32_bf16 v[26:29], v[126:129], v[178:181], v[26:29]
	v_mfma_f32_16x16x32_bf16 v[14:17], v[106:109], v[224:227], v[14:17]
	v_mfma_f32_16x16x32_bf16 v[10:13], v[126:129], v[224:227], v[10:13]
	v_mfma_f32_16x16x32_bf16 v[62:65], v[110:113], v[166:169], v[62:65]
	v_mfma_f32_16x16x32_bf16 v[58:61], v[134:137], v[166:169], v[58:61]
	v_mfma_f32_16x16x32_bf16 v[46:49], v[110:113], v[174:177], v[46:49]
	v_mfma_f32_16x16x32_bf16 v[42:45], v[134:137], v[174:177], v[42:45]
	v_mfma_f32_16x16x32_bf16 v[30:33], v[110:113], v[182:185], v[30:33]
	v_mfma_f32_16x16x32_bf16 v[26:29], v[134:137], v[182:185], v[26:29]
	v_mfma_f32_16x16x32_bf16 v[14:17], v[110:113], v[228:231], v[14:17]
	v_mfma_f32_16x16x32_bf16 v[10:13], v[134:137], v[228:231], v[10:13]
	v_mfma_f32_16x16x32_bf16 v[54:57], v[146:149], v[162:165], v[54:57]
	v_mfma_f32_16x16x32_bf16 v[50:53], v[154:157], v[162:165], v[50:53]
	v_mfma_f32_16x16x32_bf16 v[38:41], v[146:149], v[170:173], v[38:41]
	v_mfma_f32_16x16x32_bf16 v[34:37], v[154:157], v[170:173], v[34:37]
	v_mfma_f32_16x16x32_bf16 v[22:25], v[146:149], v[178:181], v[22:25]
	v_mfma_f32_16x16x32_bf16 v[18:21], v[154:157], v[178:181], v[18:21]
	v_mfma_f32_16x16x32_bf16 v[6:9], v[146:149], v[224:227], v[6:9]
	v_mfma_f32_16x16x32_bf16 v[2:5], v[154:157], v[224:227], v[2:5]
	v_mfma_f32_16x16x32_bf16 v[54:57], v[150:153], v[166:169], v[54:57]
	v_mfma_f32_16x16x32_bf16 v[50:53], v[158:161], v[166:169], v[50:53]
	v_mfma_f32_16x16x32_bf16 v[38:41], v[150:153], v[174:177], v[38:41]
	v_mfma_f32_16x16x32_bf16 v[34:37], v[158:161], v[174:177], v[34:37]
	v_mfma_f32_16x16x32_bf16 v[22:25], v[150:153], v[182:185], v[22:25]
	v_mfma_f32_16x16x32_bf16 v[18:21], v[158:161], v[182:185], v[18:21]
	v_mfma_f32_16x16x32_bf16 v[6:9], v[150:153], v[228:231], v[6:9]
	v_mfma_f32_16x16x32_bf16 v[2:5], v[158:161], v[228:231], v[2:5]
	s_barrier
	s_setprio 0
	s_add_i32 s62, s62, 2
	s_add_u32 s7, s7, 0x100
	s_addc_u32 s47, s47, 0
	s_cmp_gt_u32 s62, 41
	s_mov_b64 s[44:45], s[0:1]
	.p2align 6

.Lrb7_skip:
	s_add_u32 s42, s40, 0xfffc0080
	s_addc_u32 s43, s41, -1
	s_add_i32 s54, 0, 0x10000
	s_cmp_eq_u32 s53, 12
	s_cselect_b32 s49, s7, s43
	s_cselect_b32 s48, s23, s42
	v_add_u32_e32 v0, s54, v160
	s_cselect_b32 s43, s21, s52
	s_cselect_b32 s42, s50, s51
	s_add_i32 s65, 0, 0x14000
	ds_read_b128 v[142:145], v0
	ds_read_b128 v[146:149], v0 offset:1024
	ds_read_b128 v[150:153], v0 offset:2048
	ds_read_b128 v[154:157], v0 offset:3072
	v_add_u32_e32 v0, s65, v160
	ds_read_b128 v[162:165], v0
	ds_read_b128 v[166:169], v0 offset:1024
	ds_read_b128 v[170:173], v0 offset:2048
	ds_read_b128 v[174:177], v0 offset:3072
	v_lshl_add_u64 v[228:229], s[40:41], 0, v[138:139]
	s_add_i32 m0, s57, 0xc000
	ds_read_b128 v[178:181], v161
	ds_read_b128 v[182:185], v161 offset:1024
	ds_read_b128 v[204:207], v161 offset:2048
	ds_read_b128 v[208:211], v161 offset:3072
	ds_read_b128 v[212:215], v161 offset:4096
	ds_read_b128 v[216:219], v161 offset:5120
	ds_read_b128 v[220:223], v161 offset:6144
	ds_read_b128 v[224:227], v161 offset:7168
	global_load_lds_dwordx4 v[228:229], off
	v_lshl_add_u64 v[228:229], s[40:41], 0, v[140:141]
	s_add_i32 m0, s57, 0xe000
	s_nop 0
	global_load_lds_dwordx4 v[228:229], off
	s_waitcnt vmcnt(8)
	s_waitcnt lgkmcnt(0)
	s_setprio 1
	s_barrier
	v_mfma_f32_16x16x32_bf16 v[126:129], v[142:145], v[178:181], 0
	v_mfma_f32_16x16x32_bf16 v[122:125], v[150:153], v[178:181], 0
	v_mfma_f32_16x16x32_bf16 v[110:113], v[142:145], v[204:207], 0
	v_mfma_f32_16x16x32_bf16 v[106:109], v[150:153], v[204:207], 0
	v_mfma_f32_16x16x32_bf16 v[94:97], v[142:145], v[212:215], 0
	v_mfma_f32_16x16x32_bf16 v[90:93], v[150:153], v[212:215], 0
	v_mfma_f32_16x16x32_bf16 v[78:81], v[142:145], v[220:223], 0
	v_mfma_f32_16x16x32_bf16 v[74:77], v[150:153], v[220:223], 0
	v_mfma_f32_16x16x32_bf16 v[126:129], v[146:149], v[182:185], v[126:129]
	v_mfma_f32_16x16x32_bf16 v[122:125], v[154:157], v[182:185], v[122:125]
	v_mfma_f32_16x16x32_bf16 v[110:113], v[146:149], v[208:211], v[110:113]
	v_mfma_f32_16x16x32_bf16 v[106:109], v[154:157], v[208:211], v[106:109]
	v_mfma_f32_16x16x32_bf16 v[94:97], v[146:149], v[216:219], v[94:97]
	v_mfma_f32_16x16x32_bf16 v[90:93], v[154:157], v[216:219], v[90:93]
	v_mfma_f32_16x16x32_bf16 v[78:81], v[146:149], v[224:227], v[78:81]
	v_mfma_f32_16x16x32_bf16 v[74:77], v[154:157], v[224:227], v[74:77]
	v_mfma_f32_16x16x32_bf16 v[118:121], v[162:165], v[178:181], 0
	v_mfma_f32_16x16x32_bf16 v[114:117], v[170:173], v[178:181], 0
	v_mfma_f32_16x16x32_bf16 v[102:105], v[162:165], v[204:207], 0
	v_mfma_f32_16x16x32_bf16 v[98:101], v[170:173], v[204:207], 0
	v_mfma_f32_16x16x32_bf16 v[86:89], v[162:165], v[212:215], 0
	v_mfma_f32_16x16x32_bf16 v[82:85], v[170:173], v[212:215], 0
	v_mfma_f32_16x16x32_bf16 v[70:73], v[162:165], v[220:223], 0
	v_mfma_f32_16x16x32_bf16 v[66:69], v[170:173], v[220:223], 0
	v_mfma_f32_16x16x32_bf16 v[118:121], v[166:169], v[182:185], v[118:121]
	v_mfma_f32_16x16x32_bf16 v[114:117], v[174:177], v[182:185], v[114:117]
	v_mfma_f32_16x16x32_bf16 v[102:105], v[166:169], v[208:211], v[102:105]
	v_mfma_f32_16x16x32_bf16 v[98:101], v[174:177], v[208:211], v[98:101]
	v_mfma_f32_16x16x32_bf16 v[86:89], v[166:169], v[216:219], v[86:89]
	v_mfma_f32_16x16x32_bf16 v[82:85], v[174:177], v[216:219], v[82:85]
	v_mfma_f32_16x16x32_bf16 v[70:73], v[166:169], v[224:227], v[70:73]
	v_mfma_f32_16x16x32_bf16 v[66:69], v[174:177], v[224:227], v[66:69]
	s_barrier
	s_setprio 0
	s_add_i32 s54, s54, s56
	v_lshl_add_u64 v[228:229], s[42:43], 0, v[134:135]
	s_mov_b32 m0, s54
	ds_read_b128 v[178:181], v161 offset:16384
	ds_read_b128 v[182:185], v161 offset:17408
	ds_read_b128 v[204:207], v161 offset:18432
	ds_read_b128 v[208:211], v161 offset:19456
	ds_read_b128 v[212:215], v161 offset:20480
	ds_read_b128 v[216:219], v161 offset:21504
	ds_read_b128 v[220:223], v161 offset:22528
	ds_read_b128 v[224:227], v161 offset:23552
	global_load_lds_dwordx4 v[228:229], off
	s_add_i32 m0, s54, 0x2000
	s_add_u32 s54, s42, 0x40000
	v_lshl_add_u64 v[230:231], s[42:43], 0, v[130:131]
	s_addc_u32 s55, s43, 0
	s_add_i32 s65, s65, s56
	global_load_lds_dwordx4 v[230:231], off
	v_lshl_add_u64 v[240:241], s[54:55], 0, v[134:135]
	s_mov_b32 m0, s65
	v_lshl_add_u64 v[242:243], s[48:49], 0, v[132:133]
	global_load_lds_dwordx4 v[240:241], off
	v_lshl_add_u64 v[240:241], s[54:55], 0, v[130:131]
	s_add_i32 m0, s65, 0x2000
	s_nop 0
	global_load_lds_dwordx4 v[240:241], off
	v_lshl_add_u64 v[240:241], s[48:49], 0, v[136:137]
	s_mov_b32 m0, s57
	s_nop 0
	global_load_lds_dwordx4 v[240:241], off
	s_mov_b32 m0, s58
	s_nop 0
	global_load_lds_dwordx4 v[242:243], off
	s_waitcnt vmcnt(8)
	s_waitcnt lgkmcnt(0)
	s_setprio 1
	s_barrier
	v_mfma_f32_16x16x32_bf16 v[62:65], v[142:145], v[178:181], 0
	v_mfma_f32_16x16x32_bf16 v[58:61], v[150:153], v[178:181], 0
	v_mfma_f32_16x16x32_bf16 v[46:49], v[142:145], v[204:207], 0
	v_mfma_f32_16x16x32_bf16 v[42:45], v[150:153], v[204:207], 0
	v_mfma_f32_16x16x32_bf16 v[30:33], v[142:145], v[212:215], 0
	v_mfma_f32_16x16x32_bf16 v[26:29], v[150:153], v[212:215], 0
	v_mfma_f32_16x16x32_bf16 v[14:17], v[142:145], v[220:223], 0
	v_mfma_f32_16x16x32_bf16 v[10:13], v[150:153], v[220:223], 0
	v_mfma_f32_16x16x32_bf16 v[62:65], v[146:149], v[182:185], v[62:65]
	v_mfma_f32_16x16x32_bf16 v[58:61], v[154:157], v[182:185], v[58:61]
	v_mfma_f32_16x16x32_bf16 v[46:49], v[146:149], v[208:211], v[46:49]
	v_mfma_f32_16x16x32_bf16 v[42:45], v[154:157], v[208:211], v[42:45]
	v_mfma_f32_16x16x32_bf16 v[30:33], v[146:149], v[216:219], v[30:33]
	v_mfma_f32_16x16x32_bf16 v[26:29], v[154:157], v[216:219], v[26:29]
	v_mfma_f32_16x16x32_bf16 v[14:17], v[146:149], v[224:227], v[14:17]
	v_mfma_f32_16x16x32_bf16 v[10:13], v[154:157], v[224:227], v[10:13]
	v_mfma_f32_16x16x32_bf16 v[54:57], v[162:165], v[178:181], 0
	v_mfma_f32_16x16x32_bf16 v[50:53], v[170:173], v[178:181], 0
	v_mfma_f32_16x16x32_bf16 v[38:41], v[162:165], v[204:207], 0
	v_mfma_f32_16x16x32_bf16 v[34:37], v[170:173], v[204:207], 0
	v_mfma_f32_16x16x32_bf16 v[22:25], v[162:165], v[212:215], 0
	v_mfma_f32_16x16x32_bf16 v[18:21], v[170:173], v[212:215], 0
	v_mfma_f32_16x16x32_bf16 v[6:9], v[162:165], v[220:223], 0
	v_mfma_f32_16x16x32_bf16 v[2:5], v[170:173], v[220:223], 0
	v_mfma_f32_16x16x32_bf16 v[54:57], v[166:169], v[182:185], v[54:57]
	v_mfma_f32_16x16x32_bf16 v[50:53], v[174:177], v[182:185], v[50:53]
	v_mfma_f32_16x16x32_bf16 v[38:41], v[166:169], v[208:211], v[38:41]
	v_mfma_f32_16x16x32_bf16 v[34:37], v[174:177], v[208:211], v[34:37]
	v_mfma_f32_16x16x32_bf16 v[22:25], v[166:169], v[216:219], v[22:25]
	v_mfma_f32_16x16x32_bf16 v[18:21], v[174:177], v[216:219], v[18:21]
	v_mfma_f32_16x16x32_bf16 v[6:9], v[166:169], v[224:227], v[6:9]
	v_mfma_f32_16x16x32_bf16 v[2:5], v[174:177], v[224:227], v[2:5]
	s_barrier
	s_setprio 0
	s_add_i32 s54, 0, 0x18000
	v_add_u32_e32 v0, s54, v160
	s_add_i32 s55, 0, 0x1c000
	ds_read_b128 v[142:145], v0
	ds_read_b128 v[146:149], v0 offset:1024
	ds_read_b128 v[150:153], v0 offset:2048
	ds_read_b128 v[154:157], v0 offset:3072
	v_add_u32_e32 v0, s55, v160
	ds_read_b128 v[162:165], v0
	ds_read_b128 v[166:169], v0 offset:1024
	ds_read_b128 v[170:173], v0 offset:2048
	ds_read_b128 v[174:177], v0 offset:3072
	s_add_u32 s48, s48, 0x40000
	s_addc_u32 s49, s49, 0
	s_mov_b32 m0, s59
	v_lshl_add_u64 v[244:245], s[48:49], 0, v[136:137]
	ds_read_b128 v[178:181], v161 offset:32768
	ds_read_b128 v[182:185], v161 offset:33792
	ds_read_b128 v[204:207], v161 offset:34816
	ds_read_b128 v[208:211], v161 offset:35840
	ds_read_b128 v[212:215], v161 offset:36864
	ds_read_b128 v[216:219], v161 offset:37888
	ds_read_b128 v[220:223], v161 offset:38912
	ds_read_b128 v[224:227], v161 offset:39936
	global_load_lds_dwordx4 v[244:245], off
	v_lshl_add_u64 v[244:245], s[48:49], 0, v[132:133]
	s_mov_b32 m0, s60
	s_nop 0
	global_load_lds_dwordx4 v[244:245], off
	s_waitcnt vmcnt(8)
	s_waitcnt lgkmcnt(0)
	s_setprio 1
	s_barrier
	v_mfma_f32_16x16x32_bf16 v[126:129], v[142:145], v[178:181], v[126:129]
	v_mfma_f32_16x16x32_bf16 v[122:125], v[150:153], v[178:181], v[122:125]
	v_mfma_f32_16x16x32_bf16 v[110:113], v[142:145], v[204:207], v[110:113]
	v_mfma_f32_16x16x32_bf16 v[106:109], v[150:153], v[204:207], v[106:109]
	v_mfma_f32_16x16x32_bf16 v[94:97], v[142:145], v[212:215], v[94:97]
	v_mfma_f32_16x16x32_bf16 v[90:93], v[150:153], v[212:215], v[90:93]
	v_mfma_f32_16x16x32_bf16 v[78:81], v[142:145], v[220:223], v[78:81]
	v_mfma_f32_16x16x32_bf16 v[74:77], v[150:153], v[220:223], v[74:77]
	v_mfma_f32_16x16x32_bf16 v[126:129], v[146:149], v[182:185], v[126:129]
	v_mfma_f32_16x16x32_bf16 v[122:125], v[154:157], v[182:185], v[122:125]
	v_mfma_f32_16x16x32_bf16 v[110:113], v[146:149], v[208:211], v[110:113]
	v_mfma_f32_16x16x32_bf16 v[106:109], v[154:157], v[208:211], v[106:109]
	v_mfma_f32_16x16x32_bf16 v[94:97], v[146:149], v[216:219], v[94:97]
	v_mfma_f32_16x16x32_bf16 v[90:93], v[154:157], v[216:219], v[90:93]
	v_mfma_f32_16x16x32_bf16 v[78:81], v[146:149], v[224:227], v[78:81]
	v_mfma_f32_16x16x32_bf16 v[74:77], v[154:157], v[224:227], v[74:77]
	v_mfma_f32_16x16x32_bf16 v[118:121], v[162:165], v[178:181], v[118:121]
	v_mfma_f32_16x16x32_bf16 v[114:117], v[170:173], v[178:181], v[114:117]
	v_mfma_f32_16x16x32_bf16 v[102:105], v[162:165], v[204:207], v[102:105]
	v_mfma_f32_16x16x32_bf16 v[98:101], v[170:173], v[204:207], v[98:101]
	v_mfma_f32_16x16x32_bf16 v[86:89], v[162:165], v[212:215], v[86:89]
	v_mfma_f32_16x16x32_bf16 v[82:85], v[170:173], v[212:215], v[82:85]
	v_mfma_f32_16x16x32_bf16 v[70:73], v[162:165], v[220:223], v[70:73]
	v_mfma_f32_16x16x32_bf16 v[66:69], v[170:173], v[220:223], v[66:69]
	v_mfma_f32_16x16x32_bf16 v[118:121], v[166:169], v[182:185], v[118:121]
	v_mfma_f32_16x16x32_bf16 v[114:117], v[174:177], v[182:185], v[114:117]
	v_mfma_f32_16x16x32_bf16 v[102:105], v[166:169], v[208:211], v[102:105]
	v_mfma_f32_16x16x32_bf16 v[98:101], v[174:177], v[208:211], v[98:101]
	v_mfma_f32_16x16x32_bf16 v[86:89], v[166:169], v[216:219], v[86:89]
	v_mfma_f32_16x16x32_bf16 v[82:85], v[174:177], v[216:219], v[82:85]
	v_mfma_f32_16x16x32_bf16 v[70:73], v[166:169], v[224:227], v[70:73]
	v_mfma_f32_16x16x32_bf16 v[66:69], v[174:177], v[224:227], v[66:69]
	s_barrier
	s_setprio 0
	s_add_i32 s48, s54, s56
	v_lshl_add_u64 v[228:229], v[228:229], 0, s[16:17]
	s_mov_b32 m0, s48
	ds_read_b128 v[178:181], v161 offset:49152
	ds_read_b128 v[182:185], v161 offset:50176
	ds_read_b128 v[204:207], v161 offset:51200
	ds_read_b128 v[208:211], v161 offset:52224
	ds_read_b128 v[212:215], v161 offset:53248
	ds_read_b128 v[216:219], v161 offset:54272
	ds_read_b128 v[220:223], v161 offset:55296
	ds_read_b128 v[224:227], v161 offset:56320
	global_load_lds_dwordx4 v[228:229], off
	s_add_i32 m0, s48, 0x2000
	s_add_u32 s42, s42, 0x40080
	v_lshl_add_u64 v[228:229], v[230:231], 0, s[16:17]
	s_addc_u32 s43, s43, 0
	s_add_i32 s48, s55, s56
	global_load_lds_dwordx4 v[228:229], off
	v_lshl_add_u64 v[228:229], s[42:43], 0, v[134:135]
	s_mov_b32 m0, s48
	s_nop 0
	global_load_lds_dwordx4 v[228:229], off
	v_lshl_add_u64 v[228:229], s[42:43], 0, v[130:131]
	s_add_i32 m0, s48, 0x2000
	s_nop 0
	global_load_lds_dwordx4 v[228:229], off
	v_lshl_add_u64 v[228:229], v[240:241], 0, s[16:17]
	s_mov_b32 m0, s63
	s_nop 0
	global_load_lds_dwordx4 v[228:229], off
	v_lshl_add_u64 v[228:229], v[242:243], 0, s[16:17]
	s_mov_b32 m0, s64
	s_nop 0
	global_load_lds_dwordx4 v[228:229], off
	s_waitcnt vmcnt(8)
	s_waitcnt lgkmcnt(0)
	s_setprio 1
	s_barrier
	v_mfma_f32_16x16x32_bf16 v[62:65], v[142:145], v[178:181], v[62:65]
	v_mfma_f32_16x16x32_bf16 v[58:61], v[150:153], v[178:181], v[58:61]
	v_mfma_f32_16x16x32_bf16 v[46:49], v[142:145], v[204:207], v[46:49]
	v_mfma_f32_16x16x32_bf16 v[42:45], v[150:153], v[204:207], v[42:45]
	v_mfma_f32_16x16x32_bf16 v[30:33], v[142:145], v[212:215], v[30:33]
	v_mfma_f32_16x16x32_bf16 v[26:29], v[150:153], v[212:215], v[26:29]
	v_mfma_f32_16x16x32_bf16 v[14:17], v[142:145], v[220:223], v[14:17]
	v_mfma_f32_16x16x32_bf16 v[10:13], v[150:153], v[220:223], v[10:13]
	v_mfma_f32_16x16x32_bf16 v[62:65], v[146:149], v[182:185], v[62:65]
	v_mfma_f32_16x16x32_bf16 v[58:61], v[154:157], v[182:185], v[58:61]
	v_mfma_f32_16x16x32_bf16 v[46:49], v[146:149], v[208:211], v[46:49]
	v_mfma_f32_16x16x32_bf16 v[42:45], v[154:157], v[208:211], v[42:45]
	v_mfma_f32_16x16x32_bf16 v[30:33], v[146:149], v[216:219], v[30:33]
	v_mfma_f32_16x16x32_bf16 v[26:29], v[154:157], v[216:219], v[26:29]
	v_mfma_f32_16x16x32_bf16 v[14:17], v[146:149], v[224:227], v[14:17]
	v_mfma_f32_16x16x32_bf16 v[10:13], v[154:157], v[224:227], v[10:13]
	v_mfma_f32_16x16x32_bf16 v[54:57], v[162:165], v[178:181], v[54:57]
	v_mfma_f32_16x16x32_bf16 v[50:53], v[170:173], v[178:181], v[50:53]
	v_mfma_f32_16x16x32_bf16 v[38:41], v[162:165], v[204:207], v[38:41]
	v_mfma_f32_16x16x32_bf16 v[34:37], v[170:173], v[204:207], v[34:37]
	v_mfma_f32_16x16x32_bf16 v[22:25], v[162:165], v[212:215], v[22:25]
	v_mfma_f32_16x16x32_bf16 v[18:21], v[170:173], v[212:215], v[18:21]
	v_mfma_f32_16x16x32_bf16 v[6:9], v[162:165], v[220:223], v[6:9]
	v_mfma_f32_16x16x32_bf16 v[2:5], v[170:173], v[220:223], v[2:5]
	v_mfma_f32_16x16x32_bf16 v[54:57], v[166:169], v[182:185], v[54:57]
	v_mfma_f32_16x16x32_bf16 v[50:53], v[174:177], v[182:185], v[50:53]
	v_mfma_f32_16x16x32_bf16 v[38:41], v[166:169], v[208:211], v[38:41]
	v_mfma_f32_16x16x32_bf16 v[34:37], v[174:177], v[208:211], v[34:37]
	v_mfma_f32_16x16x32_bf16 v[22:25], v[166:169], v[216:219], v[22:25]
	v_mfma_f32_16x16x32_bf16 v[18:21], v[174:177], v[216:219], v[18:21]
	v_mfma_f32_16x16x32_bf16 v[6:9], v[166:169], v[224:227], v[6:9]
	v_mfma_f32_16x16x32_bf16 v[2:5], v[174:177], v[224:227], v[2:5]
	s_barrier
	s_setprio 0
	s_add_i32 s53, s53, 2
	s_add_u32 s40, s40, 0x100
	s_addc_u32 s41, s41, 0
	s_add_u32 s51, s51, 0x100
	s_addc_u32 s52, s52, 0
	s_cmp_gt_u32 s53, 13
	.p2align 6
